# retout epilogue: 32 gate loads preloaded (16 early, 16 after the last LDS barrier) instead of load-wait round trips; hyena step-1 halo loads issued without per-load waits
# speedup vs baseline: 1.1425x; 1.0119x over previous
.LBB0_120:
	v_lshrrev_b32_e32 v11, 3, v52
	v_lshrrev_b32_e32 v12, 1, v53
	v_bfe_u32 v13, v53, 1, 3
	v_bitop3_b32 v12, v11, v12, 7 bitop3:0x78
	v_lshlrev_b32_e32 v14, 1, v50
	v_lshl_or_b32 v12, v12, 4, v14
	v_bitop3_b32 v11, v11, v13, 1 bitop3:0x36
	v_cvt_pk_bf16_f32 v2, v84, v85
	v_cvt_pk_bf16_f32 v3, v82, v83
	v_cvt_pk_bf16_f32 v4, v80, v81
	v_cvt_pk_bf16_f32 v5, v78, v79
	v_add_u32_e32 v12, 0, v12
	v_lshl_or_b32 v11, v11, 4, v14
	v_lshrrev_b32_e32 v10, 4, v133
	s_ashr_i32 s1, s3, 6
	v_cvt_pk_bf16_f32 v6, v74, v75
	v_cvt_pk_bf16_f32 v7, v72, v73
	v_cvt_pk_bf16_f32 v8, v70, v71
	v_cvt_pk_bf16_f32 v9, v68, v69
	ds_write_b128 v12, v[2:5] offset:49152
	ds_write_b128 v12, v[6:9] offset:57344
	v_cvt_pk_bf16_f32 v2, v76, v77
	v_cvt_pk_bf16_f32 v3, v66, v67
	v_cvt_pk_bf16_f32 v4, v64, v65
	v_cvt_pk_bf16_f32 v5, v54, v55
	v_add_u32_e32 v11, 0, v11
	v_bfe_u32 v78, v133, 1, 3
	v_and_b32_e32 v0, 15, v133
	v_cvt_pk_bf16_f32 v6, v62, v63
	v_cvt_pk_bf16_f32 v7, v60, v61
	v_cvt_pk_bf16_f32 v8, v58, v59
	v_cvt_pk_bf16_f32 v9, v56, v57
	ds_write_b128 v11, v[2:5] offset:49152
	ds_write_b128 v11, v[6:9] offset:57344
	v_bitop3_b32 v2, v10, v78, 3 bitop3:0x6c
	s_lshl_b32 s0, s1, 12
	s_add_i32 s3, s0, 0
	v_lshlrev_b32_e32 v134, 7, v0
	v_lshlrev_b32_e32 v135, 4, v2
	v_add_u32_e32 v79, s3, v134
	v_or_b32_e32 v10, v135, v134
	v_add_u32_e32 v6, v79, v135
	v_add_u32_e32 v80, 0, v10
	s_waitcnt lgkmcnt(0)
	s_barrier
	ds_read_b128 v[2:5], v6
	ds_read_b128 v[6:9], v6 offset:2048
	ds_read_b128 v[10:13], v80 offset:16384
	ds_read_b128 v[18:21], v80 offset:18432
	ds_read_b128 v[26:29], v80 offset:20480
	ds_read_b128 v[34:37], v80 offset:22528
	ds_read_b128 v[42:45], v80 offset:24576
	ds_read_b128 v[50:53], v80 offset:26624
	ds_read_b128 v[58:61], v80 offset:28672
	ds_read_b128 v[66:69], v80 offset:30720
	ds_read_b128 v[70:73], v80 offset:49152
	ds_read_b128 v[74:77], v80 offset:57344
	s_waitcnt lgkmcnt(1)
	v_mfma_f32_16x16x32_bf16 v[138:141], v[2:5], v[70:73], 0
	v_bfe_u32 v132, v133, 4, 2
	v_lshlrev_b32_e32 v133, 1, v133
	s_movk_i32 s3, 0x1200
	s_waitcnt lgkmcnt(0)
	v_mfma_f32_16x16x32_bf16 v[142:145], v[2:5], v[74:77], 0
	s_mov_b64 s[10:11], 0x1000
	s_movk_i32 s7, 0x1000
	s_mov_b32 s12, 0x3c800000
	v_mfma_f32_16x16x32_bf16 v[146:149], v[6:9], v[70:73], 0
	s_mov_b32 s8, 0x800000
	s_mov_b64 s[34:35], -1
	v_mfma_f32_16x16x32_bf16 v[150:153], v[6:9], v[74:77], 0
	ds_read_b128 v[70:73], v80 offset:51200
	ds_read_b128 v[74:77], v80 offset:59392
	s_waitcnt lgkmcnt(1)
	v_mfma_f32_16x16x32_bf16 v[154:157], v[2:5], v[70:73], 0
	s_waitcnt lgkmcnt(0)
	v_mfma_f32_16x16x32_bf16 v[158:161], v[2:5], v[74:77], 0
	v_mfma_f32_16x16x32_bf16 v[162:165], v[6:9], v[70:73], 0
	v_mfma_f32_16x16x32_bf16 v[166:169], v[6:9], v[74:77], 0
	ds_read_b128 v[70:73], v80 offset:53248
	ds_read_b128 v[74:77], v80 offset:61440
	s_waitcnt lgkmcnt(1)
	v_mfma_f32_16x16x32_bf16 v[170:173], v[2:5], v[70:73], 0
	s_waitcnt lgkmcnt(0)
	v_mfma_f32_16x16x32_bf16 v[176:179], v[2:5], v[74:77], 0
	v_mfma_f32_16x16x32_bf16 v[180:183], v[6:9], v[70:73], 0
	v_mfma_f32_16x16x32_bf16 v[184:187], v[6:9], v[74:77], 0
	ds_read_b128 v[70:73], v80 offset:55296
	ds_read_b128 v[74:77], v80 offset:63488
	v_mfma_f32_16x16x32_bf16 v[14:17], v[2:5], v[10:13], 0
	v_mfma_f32_16x16x32_bf16 v[22:25], v[2:5], v[18:21], 0
	v_mfma_f32_16x16x32_bf16 v[30:33], v[2:5], v[26:29], 0
	v_mfma_f32_16x16x32_bf16 v[38:41], v[2:5], v[34:37], 0
	v_mfma_f32_16x16x32_bf16 v[46:49], v[2:5], v[42:45], 0
	v_mfma_f32_16x16x32_bf16 v[54:57], v[2:5], v[50:53], 0
	v_mfma_f32_16x16x32_bf16 v[62:65], v[2:5], v[58:61], 0
	v_mfma_f32_16x16x32_bf16 v[98:101], v[2:5], v[66:69], 0
	s_waitcnt lgkmcnt(1)
	v_mfma_f32_16x16x32_bf16 v[188:191], v[2:5], v[70:73], 0
	s_waitcnt lgkmcnt(0)
	v_mfma_f32_16x16x32_bf16 v[192:195], v[2:5], v[74:77], 0
	v_bitop3_b32 v2, v132, v78, 4 bitop3:0x36
	v_lshlrev_b32_e32 v136, 4, v2
	v_add_u32_e32 v2, v79, v136
	ds_read_b128 v[208:211], v2
	ds_read_b128 v[212:215], v2 offset:2048
	v_or_b32_e32 v2, v136, v134
	v_add_u32_e32 v137, 0, v2
	ds_read_b128 v[2:5], v137 offset:16384
	v_mfma_f32_16x16x32_bf16 v[10:13], v[6:9], v[10:13], 0
	v_lshlrev_b32_e32 v132, 2, v132
	v_lshl_or_b32 v132, s1, 5, v132
	v_and_b32_e32 v232, 15, v207
	v_lshlrev_b32_e32 v232, 1, v232
	v_mov_b32_e32 v233, 0
	v_mov_b32_e32 v247, 0
	v_or_b32_e32 v246, 0, v132
	v_add_u32_e32 v246, s6, v246
	v_mul_u32_u24_e32 v246, 0x1200, v246
	v_lshl_add_u64 v[248:249], s[92:93], 0, v[246:247]
	v_lshl_add_u64 v[248:249], v[248:249], 0, s[26:27]
	v_lshl_add_u64 v[248:249], v[248:249], 0, v[232:233]
	v_lshl_add_u64 v[248:249], v[248:249], 0, s[10:11]
	global_load_ushort v216, v[248:249], off
	global_load_ushort v217, v[248:249], off offset:32
	global_load_ushort v218, v[248:249], off offset:64
	global_load_ushort v219, v[248:249], off offset:96
	v_or_b32_e32 v246, 1, v132
	v_add_u32_e32 v246, s6, v246
	v_mul_u32_u24_e32 v246, 0x1200, v246
	v_lshl_add_u64 v[248:249], s[92:93], 0, v[246:247]
	v_lshl_add_u64 v[248:249], v[248:249], 0, s[26:27]
	v_lshl_add_u64 v[248:249], v[248:249], 0, v[232:233]
	v_lshl_add_u64 v[248:249], v[248:249], 0, s[10:11]
	global_load_ushort v220, v[248:249], off
	global_load_ushort v221, v[248:249], off offset:32
	global_load_ushort v222, v[248:249], off offset:64
	global_load_ushort v223, v[248:249], off offset:96
	v_or_b32_e32 v246, 2, v132
	v_add_u32_e32 v246, s6, v246
	v_mul_u32_u24_e32 v246, 0x1200, v246
	v_lshl_add_u64 v[248:249], s[92:93], 0, v[246:247]
	v_lshl_add_u64 v[248:249], v[248:249], 0, s[26:27]
	v_lshl_add_u64 v[248:249], v[248:249], 0, v[232:233]
	v_lshl_add_u64 v[248:249], v[248:249], 0, s[10:11]
	global_load_ushort v224, v[248:249], off
	global_load_ushort v225, v[248:249], off offset:32
	global_load_ushort v226, v[248:249], off offset:64
	global_load_ushort v227, v[248:249], off offset:96
	v_or_b32_e32 v246, 3, v132
	v_add_u32_e32 v246, s6, v246
	v_mul_u32_u24_e32 v246, 0x1200, v246
	v_lshl_add_u64 v[248:249], s[92:93], 0, v[246:247]
	v_lshl_add_u64 v[248:249], v[248:249], 0, s[26:27]
	v_lshl_add_u64 v[248:249], v[248:249], 0, v[232:233]
	v_lshl_add_u64 v[248:249], v[248:249], 0, s[10:11]
	global_load_ushort v228, v[248:249], off
	global_load_ushort v229, v[248:249], off offset:32
	global_load_ushort v230, v[248:249], off offset:64
	global_load_ushort v231, v[248:249], off offset:96
	s_waitcnt lgkmcnt(0)
	v_mfma_f32_16x16x32_bf16 v[126:129], v[208:211], v[2:5], v[14:17]
	v_mfma_f32_16x16x32_bf16 v[94:97], v[212:215], v[2:5], v[10:13]
	ds_read_b128 v[2:5], v137 offset:18432
	v_mfma_f32_16x16x32_bf16 v[18:21], v[6:9], v[18:21], 0
	s_waitcnt lgkmcnt(0)
	v_mfma_f32_16x16x32_bf16 v[122:125], v[208:211], v[2:5], v[22:25]
	v_mfma_f32_16x16x32_bf16 v[90:93], v[212:215], v[2:5], v[18:21]
	ds_read_b128 v[2:5], v137 offset:20480
	v_mfma_f32_16x16x32_bf16 v[26:29], v[6:9], v[26:29], 0
	s_waitcnt lgkmcnt(0)
	v_mfma_f32_16x16x32_bf16 v[118:121], v[208:211], v[2:5], v[30:33]
	v_mfma_f32_16x16x32_bf16 v[86:89], v[212:215], v[2:5], v[26:29]
	ds_read_b128 v[2:5], v137 offset:22528
	v_mfma_f32_16x16x32_bf16 v[34:37], v[6:9], v[34:37], 0
	s_waitcnt lgkmcnt(0)
	v_mfma_f32_16x16x32_bf16 v[114:117], v[208:211], v[2:5], v[38:41]
	v_mfma_f32_16x16x32_bf16 v[82:85], v[212:215], v[2:5], v[34:37]
	ds_read_b128 v[2:5], v137 offset:24576
	v_mfma_f32_16x16x32_bf16 v[42:45], v[6:9], v[42:45], 0
	s_waitcnt lgkmcnt(0)
	v_mfma_f32_16x16x32_bf16 v[110:113], v[208:211], v[2:5], v[46:49]
	v_mfma_f32_16x16x32_bf16 v[78:81], v[212:215], v[2:5], v[42:45]
	ds_read_b128 v[2:5], v137 offset:26624
	v_mfma_f32_16x16x32_bf16 v[50:53], v[6:9], v[50:53], 0
	v_mfma_f32_16x16x32_bf16 v[200:203], v[6:9], v[74:77], 0
	s_waitcnt lgkmcnt(0)
	v_mfma_f32_16x16x32_bf16 v[106:109], v[208:211], v[2:5], v[54:57]
	v_mfma_f32_16x16x32_bf16 v[74:77], v[212:215], v[2:5], v[50:53]
	ds_read_b128 v[2:5], v137 offset:28672
	v_mfma_f32_16x16x32_bf16 v[58:61], v[6:9], v[58:61], 0
	v_mfma_f32_16x16x32_bf16 v[196:199], v[6:9], v[70:73], 0
	s_waitcnt lgkmcnt(0)
	v_mfma_f32_16x16x32_bf16 v[102:105], v[208:211], v[2:5], v[62:65]
	v_mfma_f32_16x16x32_bf16 v[70:73], v[212:215], v[2:5], v[58:61]
	ds_read_b128 v[2:5], v137 offset:30720
	v_mfma_f32_16x16x32_bf16 v[66:69], v[6:9], v[66:69], 0
	s_waitcnt lgkmcnt(0)
	v_mfma_f32_16x16x32_bf16 v[98:101], v[208:211], v[2:5], v[98:101]
	v_mfma_f32_16x16x32_bf16 v[66:69], v[212:215], v[2:5], v[66:69]
	ds_read_b128 v[2:5], v137 offset:49152
	ds_read_b128 v[6:9], v137 offset:57344
	ds_read_b128 v[10:13], v137 offset:51200
	ds_read_b128 v[14:17], v137 offset:59392
	ds_read_b128 v[18:21], v137 offset:53248
	ds_read_b128 v[22:25], v137 offset:61440
	s_waitcnt lgkmcnt(5)
	v_mfma_f32_16x16x32_bf16 v[34:37], v[208:211], v[2:5], v[138:141]
	ds_read_b128 v[26:29], v137 offset:55296
	s_nop 1
	ds_read_b128 v[138:141], v137 offset:63488
	v_sub_u32_e32 v137, v132, v0
	v_cmp_lt_i32_e32 vcc, -1, v137
	s_waitcnt lgkmcnt(1)
	v_mfma_f32_16x16x32_bf16 v[62:65], v[208:211], v[26:29], v[188:191]
	s_waitcnt lgkmcnt(0)
	s_barrier
	v_mfma_f32_16x16x32_bf16 v[58:61], v[208:211], v[138:141], v[192:195]
	v_mfma_f32_16x16x32_bf16 v[30:33], v[212:215], v[26:29], v[196:199]
	v_mfma_f32_16x16x32_bf16 v[26:29], v[212:215], v[138:141], v[200:203]
	v_cvt_f32_u32_e32 v138, v137
	v_lshlrev_b32_e32 v140, 7, v132
	v_mul_f32_e32 v138, v138, v131
	v_mul_f32_e32 v138, 0xbfb8aa3b, v138
	v_exp_f32_e32 v138, v138
	v_mfma_f32_16x16x32_bf16 v[2:5], v[212:215], v[2:5], v[146:149]
	v_add_f32_e32 v138, 0, v138
	v_cndmask_b32_e32 v139, 0, v138, vcc
	v_cmp_gt_i32_e32 vcc, 1, v137
	v_sub_u32_e32 v137, 0, v137
	v_cvt_f32_u32_e32 v137, v137
	v_mfma_f32_16x16x32_bf16 v[38:41], v[208:211], v[6:9], v[142:145]
	v_mul_f32_e32 v137, v137, v130
	v_mul_f32_e32 v137, 0xbfb8aa3b, v137
	v_exp_f32_e32 v137, v137
	v_mfma_f32_16x16x32_bf16 v[6:9], v[212:215], v[6:9], v[150:153]
	v_add_f32_e32 v137, v137, v139
	v_lshlrev_b32_e32 v139, 2, v132
	v_cndmask_b32_e32 v138, v138, v137, vcc
	v_bitop3_b32 v137, v139, 56, v0 bitop3:0xc8
	v_mul_f32_e32 v126, v138, v126
	v_lshl_add_u32 v141, v137, 1, 0
	v_and_b32_e32 v137, 14, v133
	v_cvt_pk_bf16_f32 v126, v126, s0
	v_add3_u32 v146, v141, v140, v137
	v_or_b32_e32 v133, 1, v132
	ds_write_b16 v146, v126
	v_sub_u32_e32 v126, v133, v0
	v_cvt_f32_u32_e32 v141, v126
	v_cmp_lt_i32_e32 vcc, -1, v126
	v_mul_f32_e32 v90, v138, v90
	v_cvt_pk_bf16_f32 v90, v90, s0
	v_mul_f32_e32 v141, v141, v131
	v_mul_f32_e32 v141, 0xbfb8aa3b, v141
	v_exp_f32_e32 v141, v141
	v_mfma_f32_16x16x32_bf16 v[42:45], v[208:211], v[10:13], v[154:157]
	v_add_f32_e32 v141, 0, v141
	v_cndmask_b32_e32 v142, 0, v141, vcc
	v_cmp_gt_i32_e32 vcc, 1, v126
	v_sub_u32_e32 v126, 0, v126
	v_cvt_f32_u32_e32 v126, v126
	v_mfma_f32_16x16x32_bf16 v[46:49], v[208:211], v[14:17], v[158:161]
	v_mul_f32_e32 v126, v126, v130
	v_mul_f32_e32 v126, 0xbfb8aa3b, v126
	v_exp_f32_e32 v126, v126
	v_mfma_f32_16x16x32_bf16 v[50:53], v[208:211], v[18:21], v[170:173]
	v_add_f32_e32 v126, v126, v142
	v_cndmask_b32_e32 v126, v141, v126, vcc
	v_lshlrev_b32_e32 v141, 2, v133
	v_mul_f32_e32 v126, v126, v127
	v_bitop3_b32 v127, v141, 56, v0 bitop3:0xc8
	v_lshl_add_u32 v127, v127, 1, 0
	v_lshlrev_b32_e32 v142, 7, v133
	v_cvt_pk_bf16_f32 v126, v126, s0
	v_add3_u32 v147, v127, v142, v137
	v_or_b32_e32 v127, 2, v132
	ds_write_b16 v147, v126
	v_sub_u32_e32 v126, v127, v0
	v_cvt_f32_u32_e32 v143, v126
	v_cmp_lt_i32_e32 vcc, -1, v126
	v_mfma_f32_16x16x32_bf16 v[54:57], v[208:211], v[22:25], v[176:179]
	v_mul_f32_e32 v143, v143, v131
	v_mul_f32_e32 v143, 0xbfb8aa3b, v143
	v_exp_f32_e32 v143, v143
	v_mfma_f32_16x16x32_bf16 v[10:13], v[212:215], v[10:13], v[162:165]
	v_add_f32_e32 v143, 0, v143
	v_cndmask_b32_e32 v144, 0, v143, vcc
	v_cmp_gt_i32_e32 vcc, 1, v126
	v_sub_u32_e32 v126, 0, v126
	v_cvt_f32_u32_e32 v126, v126
	v_mfma_f32_16x16x32_bf16 v[14:17], v[212:215], v[14:17], v[166:169]
	v_mul_f32_e32 v126, v126, v130
	v_mul_f32_e32 v126, 0xbfb8aa3b, v126
	v_exp_f32_e32 v126, v126
	v_mfma_f32_16x16x32_bf16 v[18:21], v[212:215], v[18:21], v[180:183]
	v_add_f32_e32 v126, v126, v144
	v_cndmask_b32_e32 v126, v143, v126, vcc
	v_lshlrev_b32_e32 v143, 2, v127
	v_mul_f32_e32 v126, v126, v128
	v_bitop3_b32 v128, v143, 56, v0 bitop3:0x48
	v_lshl_add_u32 v128, v128, 1, 0
	v_lshlrev_b32_e32 v144, 7, v127
	v_cvt_pk_bf16_f32 v126, v126, s0
	v_add3_u32 v148, v128, v144, v137
	ds_write_b16 v148, v126
	v_or_b32_e32 v126, 3, v132
	v_sub_u32_e32 v128, v126, v0
	v_cvt_f32_u32_e32 v145, v128
	v_cmp_lt_i32_e32 vcc, -1, v128
	v_mfma_f32_16x16x32_bf16 v[22:25], v[212:215], v[22:25], v[184:187]
	v_mul_f32_e32 v145, v145, v131
	v_mul_f32_e32 v145, 0xbfb8aa3b, v145
	v_exp_f32_e32 v145, v145
	s_nop 0
	v_add_f32_e32 v145, 0, v145
	v_cndmask_b32_e32 v149, 0, v145, vcc
	v_cmp_gt_i32_e32 vcc, 1, v128
	v_sub_u32_e32 v128, 0, v128
	v_cvt_f32_u32_e32 v128, v128
	v_mul_f32_e32 v128, v128, v130
	v_mul_f32_e32 v128, 0xbfb8aa3b, v128
	v_exp_f32_e32 v128, v128
	s_nop 0
	v_add_f32_e32 v128, v128, v149
	v_cndmask_b32_e32 v128, v145, v128, vcc
	v_mul_f32_e32 v128, v128, v129
	v_lshlrev_b32_e32 v129, 2, v126
	v_bitop3_b32 v145, v129, 56, v0 bitop3:0x48
	v_lshl_add_u32 v149, v145, 1, 0
	v_lshlrev_b32_e32 v145, 7, v126
	v_cvt_pk_bf16_f32 v128, v128, s0
	v_add3_u32 v149, v149, v145, v137
	ds_write_b16 v149, v128
	v_or_b32_e32 v128, 16, v0
	v_sub_u32_e32 v150, v132, v128
	v_cvt_f32_u32_e32 v151, v150
	v_cmp_lt_i32_e32 vcc, -1, v150
	v_mul_f32_e32 v151, v151, v131
	v_mul_f32_e32 v151, 0xbfb8aa3b, v151
	v_exp_f32_e32 v151, v151
	s_nop 0
	v_add_f32_e32 v151, 0, v151
	v_cndmask_b32_e32 v152, 0, v151, vcc
	v_cmp_gt_i32_e32 vcc, 1, v150
	v_sub_u32_e32 v150, 0, v150
	v_cvt_f32_u32_e32 v150, v150
	v_mul_f32_e32 v150, v150, v130
	v_mul_f32_e32 v150, 0xbfb8aa3b, v150
	v_exp_f32_e32 v150, v150
	s_nop 0
	v_add_f32_e32 v150, v150, v152
	v_cndmask_b32_e32 v150, v151, v150, vcc
	v_mul_f32_e32 v122, v150, v122
	v_bitop3_b32 v150, v139, 56, v128 bitop3:0x48
	v_lshl_add_u32 v150, v150, 1, 0
	v_cvt_pk_bf16_f32 v122, v122, s0
	v_add3_u32 v150, v150, v140, v137
	ds_write_b16 v150, v122
	v_sub_u32_e32 v122, v133, v128
	v_cvt_f32_u32_e32 v150, v122
	v_cmp_lt_i32_e32 vcc, -1, v122
	v_mul_f32_e32 v150, v150, v131
	v_mul_f32_e32 v150, 0xbfb8aa3b, v150
	v_exp_f32_e32 v150, v150
	s_nop 0
	v_add_f32_e32 v150, 0, v150
	v_cndmask_b32_e32 v151, 0, v150, vcc
	v_cmp_gt_i32_e32 vcc, 1, v122
	v_sub_u32_e32 v122, 0, v122
	v_cvt_f32_u32_e32 v122, v122
	v_mul_f32_e32 v122, v122, v130
	v_mul_f32_e32 v122, 0xbfb8aa3b, v122
	v_exp_f32_e32 v122, v122
	s_nop 0
	v_add_f32_e32 v122, v122, v151
	v_cndmask_b32_e32 v122, v150, v122, vcc
	v_mul_f32_e32 v122, v122, v123
	v_bitop3_b32 v123, v141, 56, v128 bitop3:0x48
	v_lshl_add_u32 v123, v123, 1, 0
	v_cvt_pk_bf16_f32 v122, v122, s0
	v_add3_u32 v123, v123, v142, v137
	ds_write_b16 v123, v122
	v_sub_u32_e32 v122, v127, v128
	v_cvt_f32_u32_e32 v123, v122
	v_cmp_lt_i32_e32 vcc, -1, v122
	v_mul_f32_e32 v123, v123, v131
	v_mul_f32_e32 v123, 0xbfb8aa3b, v123
	v_exp_f32_e32 v123, v123
	s_nop 0
	v_add_f32_e32 v123, 0, v123
	v_cndmask_b32_e32 v150, 0, v123, vcc
	v_cmp_gt_i32_e32 vcc, 1, v122
	v_sub_u32_e32 v122, 0, v122
	v_cvt_f32_u32_e32 v122, v122
	v_mul_f32_e32 v122, v122, v130
	v_mul_f32_e32 v122, 0xbfb8aa3b, v122
	v_exp_f32_e32 v122, v122
	s_nop 0
	v_add_f32_e32 v122, v122, v150
	v_cndmask_b32_e32 v122, v123, v122, vcc
	v_bitop3_b32 v123, v143, 56, v128 bitop3:0x48
	v_mul_f32_e32 v122, v122, v124
	v_lshl_add_u32 v123, v123, 1, 0
	v_cvt_pk_bf16_f32 v122, v122, s0
	v_add3_u32 v123, v123, v144, v137
	ds_write_b16 v123, v122
	v_sub_u32_e32 v122, v126, v128
	v_cvt_f32_u32_e32 v123, v122
	v_cmp_lt_i32_e32 vcc, -1, v122
	v_mul_f32_e32 v123, v123, v131
	v_mul_f32_e32 v123, 0xbfb8aa3b, v123
	v_exp_f32_e32 v123, v123
	s_nop 0
	v_add_f32_e32 v123, 0, v123
	v_cndmask_b32_e32 v124, 0, v123, vcc
	v_cmp_gt_i32_e32 vcc, 1, v122
	v_sub_u32_e32 v122, 0, v122
	v_cvt_f32_u32_e32 v122, v122
	v_mul_f32_e32 v122, v122, v130
	v_mul_f32_e32 v122, 0xbfb8aa3b, v122
	v_exp_f32_e32 v122, v122
	s_nop 0
	v_add_f32_e32 v122, v122, v124
	v_cndmask_b32_e32 v122, v123, v122, vcc
	v_bitop3_b32 v123, v129, 56, v128 bitop3:0x48
	v_mul_f32_e32 v122, v122, v125
	v_lshl_add_u32 v123, v123, 1, 0
	v_cvt_pk_bf16_f32 v122, v122, s0
	v_add3_u32 v123, v123, v145, v137
	ds_write_b16 v123, v122
	v_or_b32_e32 v122, 32, v0
	v_sub_u32_e32 v123, v132, v122
	v_cvt_f32_u32_e32 v124, v123
	v_cmp_lt_i32_e32 vcc, -1, v123
	v_mul_f32_e32 v124, v124, v131
	v_mul_f32_e32 v124, 0xbfb8aa3b, v124
	v_exp_f32_e32 v124, v124
	s_nop 0
	v_add_f32_e32 v124, 0, v124
	v_cndmask_b32_e32 v125, 0, v124, vcc
	v_cmp_gt_i32_e32 vcc, 1, v123
	v_sub_u32_e32 v123, 0, v123
	v_cvt_f32_u32_e32 v123, v123
	v_mul_f32_e32 v123, v123, v130
	v_mul_f32_e32 v123, 0xbfb8aa3b, v123
	v_exp_f32_e32 v123, v123
	s_nop 0
	v_add_f32_e32 v123, v123, v125
	v_cndmask_b32_e32 v123, v124, v123, vcc
	v_mul_f32_e32 v118, v123, v118
	v_bitop3_b32 v123, v139, 56, v122 bitop3:0x48
	v_lshl_add_u32 v123, v123, 1, 0
	v_cvt_pk_bf16_f32 v118, v118, s0
	v_add3_u32 v123, v123, v140, v137
	ds_write_b16 v123, v118
	v_sub_u32_e32 v118, v133, v122
	v_cvt_f32_u32_e32 v123, v118
	v_cmp_lt_i32_e32 vcc, -1, v118
	v_mul_f32_e32 v123, v123, v131
	v_mul_f32_e32 v123, 0xbfb8aa3b, v123
	v_exp_f32_e32 v123, v123
	s_nop 0
	v_add_f32_e32 v123, 0, v123
	v_cndmask_b32_e32 v124, 0, v123, vcc
	v_cmp_gt_i32_e32 vcc, 1, v118
	v_sub_u32_e32 v118, 0, v118
	v_cvt_f32_u32_e32 v118, v118
	v_mul_f32_e32 v118, v118, v130
	v_mul_f32_e32 v118, 0xbfb8aa3b, v118
	v_exp_f32_e32 v118, v118
	s_nop 0
	v_add_f32_e32 v118, v118, v124
	v_cndmask_b32_e32 v118, v123, v118, vcc
	v_mul_f32_e32 v118, v118, v119
	v_bitop3_b32 v119, v141, 56, v122 bitop3:0x48
	v_lshl_add_u32 v119, v119, 1, 0
	v_cvt_pk_bf16_f32 v118, v118, s0
	v_add3_u32 v119, v119, v142, v137
	ds_write_b16 v119, v118
	v_sub_u32_e32 v118, v127, v122
	v_cvt_f32_u32_e32 v119, v118
	v_cmp_lt_i32_e32 vcc, -1, v118
	v_add3_u32 v124, 0, v136, v134
	v_add_u32_e32 v125, s0, v124
	v_mul_f32_e32 v119, v119, v131
	v_mul_f32_e32 v119, 0xbfb8aa3b, v119
	v_exp_f32_e32 v119, v119
	s_nop 0
	v_add_f32_e32 v119, 0, v119
	v_cndmask_b32_e32 v123, 0, v119, vcc
	v_cmp_gt_i32_e32 vcc, 1, v118
	v_sub_u32_e32 v118, 0, v118
	v_cvt_f32_u32_e32 v118, v118
	v_mul_f32_e32 v118, v118, v130
	v_mul_f32_e32 v118, 0xbfb8aa3b, v118
	v_exp_f32_e32 v118, v118
	s_nop 0
	v_add_f32_e32 v118, v118, v123
	v_cndmask_b32_e32 v118, v119, v118, vcc
	v_bitop3_b32 v119, v143, 56, v122 bitop3:0x48
	v_mul_f32_e32 v118, v118, v120
	v_lshl_add_u32 v119, v119, 1, 0
	v_cvt_pk_bf16_f32 v118, v118, s0
	v_add3_u32 v119, v119, v144, v137
	ds_write_b16 v119, v118
	v_sub_u32_e32 v118, v126, v122
	v_cvt_f32_u32_e32 v119, v118
	v_cmp_lt_i32_e32 vcc, -1, v118
	v_mul_f32_e32 v119, v119, v131
	v_mul_f32_e32 v119, 0xbfb8aa3b, v119
	v_exp_f32_e32 v119, v119
	s_nop 0
	v_add_f32_e32 v119, 0, v119
	v_cndmask_b32_e32 v120, 0, v119, vcc
	v_cmp_gt_i32_e32 vcc, 1, v118
	v_sub_u32_e32 v118, 0, v118
	v_cvt_f32_u32_e32 v118, v118
	v_mul_f32_e32 v118, v118, v130
	v_mul_f32_e32 v118, 0xbfb8aa3b, v118
	v_exp_f32_e32 v118, v118
	s_nop 0
	v_add_f32_e32 v118, v118, v120
	v_cndmask_b32_e32 v118, v119, v118, vcc
	v_bitop3_b32 v119, v129, 56, v122 bitop3:0x48
	v_mul_f32_e32 v118, v118, v121
	v_lshl_add_u32 v119, v119, 1, 0
	v_cvt_pk_bf16_f32 v118, v118, s0
	v_add3_u32 v119, v119, v145, v137
	ds_write_b16 v119, v118
	v_or_b32_e32 v118, 48, v0
	v_sub_u32_e32 v119, v132, v118
	v_cvt_f32_u32_e32 v120, v119
	v_cmp_lt_i32_e32 vcc, -1, v119
	v_mul_f32_e32 v120, v120, v131
	v_mul_f32_e32 v120, 0xbfb8aa3b, v120
	v_exp_f32_e32 v120, v120
	s_nop 0
	v_add_f32_e32 v120, 0, v120
	v_cndmask_b32_e32 v121, 0, v120, vcc
	v_cmp_gt_i32_e32 vcc, 1, v119
	v_sub_u32_e32 v119, 0, v119
	v_cvt_f32_u32_e32 v119, v119
	v_mul_f32_e32 v119, v119, v130
	v_mul_f32_e32 v119, 0xbfb8aa3b, v119
	v_exp_f32_e32 v119, v119
	s_nop 0
	v_add_f32_e32 v119, v119, v121
	v_cndmask_b32_e32 v119, v120, v119, vcc
	v_mul_f32_e32 v114, v119, v114
	v_bitop3_b32 v119, v139, 56, v118 bitop3:0x48
	v_lshl_add_u32 v119, v119, 1, 0
	v_cvt_pk_bf16_f32 v114, v114, s0
	v_add3_u32 v119, v119, v140, v137
	ds_write_b16 v119, v114
	v_sub_u32_e32 v114, v133, v118
	v_cvt_f32_u32_e32 v119, v114
	v_cmp_lt_i32_e32 vcc, -1, v114
	v_mul_f32_e32 v119, v119, v131
	v_mul_f32_e32 v119, 0xbfb8aa3b, v119
	v_exp_f32_e32 v119, v119
	s_nop 0
	v_add_f32_e32 v119, 0, v119
	v_cndmask_b32_e32 v120, 0, v119, vcc
	v_cmp_gt_i32_e32 vcc, 1, v114
	v_sub_u32_e32 v114, 0, v114
	v_cvt_f32_u32_e32 v114, v114
	v_mul_f32_e32 v114, v114, v130
	v_mul_f32_e32 v114, 0xbfb8aa3b, v114
	v_exp_f32_e32 v114, v114
	s_nop 0
	v_add_f32_e32 v114, v114, v120
	v_cndmask_b32_e32 v114, v119, v114, vcc
	v_mul_f32_e32 v114, v114, v115
	v_bitop3_b32 v115, v141, 56, v118 bitop3:0x48
	v_lshl_add_u32 v115, v115, 1, 0
	v_cvt_pk_bf16_f32 v114, v114, s0
	v_add3_u32 v115, v115, v142, v137
	ds_write_b16 v115, v114
	v_sub_u32_e32 v114, v127, v118
	v_cvt_f32_u32_e32 v115, v114
	v_cmp_lt_i32_e32 vcc, -1, v114
	v_mul_f32_e32 v115, v115, v131
	v_mul_f32_e32 v115, 0xbfb8aa3b, v115
	v_exp_f32_e32 v115, v115
	s_nop 0
	v_add_f32_e32 v115, 0, v115
	v_cndmask_b32_e32 v119, 0, v115, vcc
	v_cmp_gt_i32_e32 vcc, 1, v114
	v_sub_u32_e32 v114, 0, v114
	v_cvt_f32_u32_e32 v114, v114
	v_mul_f32_e32 v114, v114, v130
	v_mul_f32_e32 v114, 0xbfb8aa3b, v114
	v_exp_f32_e32 v114, v114
	s_nop 0
	v_add_f32_e32 v114, v114, v119
	v_cndmask_b32_e32 v114, v115, v114, vcc
	v_bitop3_b32 v115, v143, 56, v118 bitop3:0x48
	v_mul_f32_e32 v114, v114, v116
	v_lshl_add_u32 v115, v115, 1, 0
	v_cvt_pk_bf16_f32 v114, v114, s0
	v_add3_u32 v115, v115, v144, v137
	ds_write_b16 v115, v114
	v_sub_u32_e32 v114, v126, v118
	v_cvt_f32_u32_e32 v115, v114
	v_cmp_lt_i32_e32 vcc, -1, v114
	v_mul_f32_e32 v115, v115, v131
	v_mul_f32_e32 v115, 0xbfb8aa3b, v115
	v_exp_f32_e32 v115, v115
	s_nop 0
	v_add_f32_e32 v115, 0, v115
	v_cndmask_b32_e32 v116, 0, v115, vcc
	v_cmp_gt_i32_e32 vcc, 1, v114
	v_sub_u32_e32 v114, 0, v114
	v_cvt_f32_u32_e32 v114, v114
	v_mul_f32_e32 v114, v114, v130
	v_mul_f32_e32 v114, 0xbfb8aa3b, v114
	v_exp_f32_e32 v114, v114
	s_nop 0
	v_add_f32_e32 v114, v114, v116
	v_cndmask_b32_e32 v114, v115, v114, vcc
	v_bitop3_b32 v115, v129, 56, v118 bitop3:0x48
	v_mul_f32_e32 v114, v114, v117
	v_lshl_add_u32 v115, v115, 1, 0
	v_cvt_pk_bf16_f32 v114, v114, s0
	v_add3_u32 v115, v115, v145, v137
	ds_write_b16 v115, v114
	v_or_b32_e32 v114, 64, v0
	v_sub_u32_e32 v115, v132, v114
	v_cvt_f32_u32_e32 v116, v115
	v_cmp_lt_i32_e32 vcc, -1, v115
	v_mul_f32_e32 v116, v116, v131
	v_mul_f32_e32 v116, 0xbfb8aa3b, v116
	v_exp_f32_e32 v116, v116
	s_nop 0
	v_add_f32_e32 v116, 0, v116
	v_cndmask_b32_e32 v117, 0, v116, vcc
	v_cmp_gt_i32_e32 vcc, 1, v115
	v_sub_u32_e32 v115, 0, v115
	v_cvt_f32_u32_e32 v115, v115
	v_mul_f32_e32 v115, v115, v130
	v_mul_f32_e32 v115, 0xbfb8aa3b, v115
	v_exp_f32_e32 v115, v115
	s_nop 0
	v_add_f32_e32 v115, v115, v117
	v_cndmask_b32_e32 v115, v116, v115, vcc
	v_mul_f32_e32 v110, v115, v110
	v_cvt_pk_bf16_f32 v110, v110, s0
	ds_write_b16 v146, v110 offset:16384
	v_sub_u32_e32 v110, v133, v114
	v_cvt_f32_u32_e32 v115, v110
	v_cmp_lt_i32_e32 vcc, -1, v110
	v_mul_f32_e32 v115, v115, v131
	v_mul_f32_e32 v115, 0xbfb8aa3b, v115
	v_exp_f32_e32 v115, v115
	s_nop 0
	v_add_f32_e32 v115, 0, v115
	v_cndmask_b32_e32 v116, 0, v115, vcc
	v_cmp_gt_i32_e32 vcc, 1, v110
	v_sub_u32_e32 v110, 0, v110
	v_cvt_f32_u32_e32 v110, v110
	v_mul_f32_e32 v110, v110, v130
	v_mul_f32_e32 v110, 0xbfb8aa3b, v110
	v_exp_f32_e32 v110, v110
	s_nop 0
	v_add_f32_e32 v110, v110, v116
	v_cndmask_b32_e32 v110, v115, v110, vcc
	v_mul_f32_e32 v110, v110, v111
	v_cvt_pk_bf16_f32 v110, v110, s0
	ds_write_b16 v147, v110 offset:16384
	v_sub_u32_e32 v110, v127, v114
	v_cvt_f32_u32_e32 v111, v110
	v_cmp_lt_i32_e32 vcc, -1, v110
	v_mul_f32_e32 v111, v111, v131
	v_mul_f32_e32 v111, 0xbfb8aa3b, v111
	v_exp_f32_e32 v111, v111
	s_nop 0
	v_add_f32_e32 v111, 0, v111
	v_cndmask_b32_e32 v115, 0, v111, vcc
	v_cmp_gt_i32_e32 vcc, 1, v110
	v_sub_u32_e32 v110, 0, v110
	v_cvt_f32_u32_e32 v110, v110
	v_mul_f32_e32 v110, v110, v130
	v_mul_f32_e32 v110, 0xbfb8aa3b, v110
	v_exp_f32_e32 v110, v110
	s_nop 0
	v_add_f32_e32 v110, v110, v115
	v_cndmask_b32_e32 v110, v111, v110, vcc
	v_mul_f32_e32 v110, v110, v112
	v_cvt_pk_bf16_f32 v110, v110, s0
	ds_write_b16 v148, v110 offset:16384
	v_sub_u32_e32 v110, v126, v114
	v_cvt_f32_u32_e32 v111, v110
	v_cmp_lt_i32_e32 vcc, -1, v110
	v_or_b32_e32 v115, 16, v132
	v_mul_f32_e32 v111, v111, v131
	v_mul_f32_e32 v111, 0xbfb8aa3b, v111
	v_exp_f32_e32 v111, v111
	s_nop 0
	v_add_f32_e32 v111, 0, v111
	v_cndmask_b32_e32 v112, 0, v111, vcc
	v_cmp_gt_i32_e32 vcc, 1, v110
	v_sub_u32_e32 v110, 0, v110
	v_cvt_f32_u32_e32 v110, v110
	v_mul_f32_e32 v110, v110, v130
	v_mul_f32_e32 v110, 0xbfb8aa3b, v110
	v_exp_f32_e32 v110, v110
	s_nop 0
	v_add_f32_e32 v110, v110, v112
	v_cndmask_b32_e32 v110, v111, v110, vcc
	v_mul_f32_e32 v110, v110, v113
	v_cvt_pk_bf16_f32 v110, v110, s0
	v_or_b32_e32 v113, 0x50, v0
	ds_write_b16 v149, v110 offset:16384
	v_sub_u32_e32 v110, v132, v113
	v_cvt_f32_u32_e32 v111, v110
	v_cmp_lt_i32_e32 vcc, -1, v110
	v_mul_f32_e32 v111, v111, v131
	v_mul_f32_e32 v111, 0xbfb8aa3b, v111
	v_exp_f32_e32 v111, v111
	s_nop 0
	v_add_f32_e32 v111, 0, v111
	v_cndmask_b32_e32 v112, 0, v111, vcc
	v_cmp_gt_i32_e32 vcc, 1, v110
	v_sub_u32_e32 v110, 0, v110
	v_cvt_f32_u32_e32 v110, v110
	v_mul_f32_e32 v110, v110, v130
	v_mul_f32_e32 v110, 0xbfb8aa3b, v110
	v_exp_f32_e32 v110, v110
	s_nop 0
	v_add_f32_e32 v110, v110, v112
	v_cndmask_b32_e32 v110, v111, v110, vcc
	v_mul_f32_e32 v106, v110, v106
	v_bitop3_b32 v110, v139, 56, v113 bitop3:0x48
	v_lshl_add_u32 v110, v110, 1, 0
	v_cvt_pk_bf16_f32 v106, v106, s0
	v_add3_u32 v110, v110, v140, v137
	ds_write_b16 v110, v106 offset:16384
	v_sub_u32_e32 v106, v133, v113
	v_cvt_f32_u32_e32 v110, v106
	v_cmp_lt_i32_e32 vcc, -1, v106
	v_or_b32_e32 v112, 17, v132
	v_mul_f32_e32 v110, v110, v131
	v_mul_f32_e32 v110, 0xbfb8aa3b, v110
	v_exp_f32_e32 v110, v110
	s_nop 0
	v_add_f32_e32 v110, 0, v110
	v_cndmask_b32_e32 v111, 0, v110, vcc
	v_cmp_gt_i32_e32 vcc, 1, v106
	v_sub_u32_e32 v106, 0, v106
	v_cvt_f32_u32_e32 v106, v106
	v_mul_f32_e32 v106, v106, v130
	v_mul_f32_e32 v106, 0xbfb8aa3b, v106
	v_exp_f32_e32 v106, v106
	s_nop 0
	v_add_f32_e32 v106, v106, v111
	v_cndmask_b32_e32 v106, v110, v106, vcc
	v_mul_f32_e32 v106, v106, v107
	v_bitop3_b32 v107, v141, 56, v113 bitop3:0x48
	v_lshl_add_u32 v107, v107, 1, 0
	v_cvt_pk_bf16_f32 v106, v106, s0
	v_add3_u32 v107, v107, v142, v137
	ds_write_b16 v107, v106 offset:16384
	v_sub_u32_e32 v106, v127, v113
	v_cvt_f32_u32_e32 v107, v106
	v_cmp_lt_i32_e32 vcc, -1, v106
	v_or_b32_e32 v111, 18, v132
	v_mul_f32_e32 v107, v107, v131
	v_mul_f32_e32 v107, 0xbfb8aa3b, v107
	v_exp_f32_e32 v107, v107
	s_nop 0
	v_add_f32_e32 v107, 0, v107
	v_cndmask_b32_e32 v110, 0, v107, vcc
	v_cmp_gt_i32_e32 vcc, 1, v106
	v_sub_u32_e32 v106, 0, v106
	v_cvt_f32_u32_e32 v106, v106
	v_mul_f32_e32 v106, v106, v130
	v_mul_f32_e32 v106, 0xbfb8aa3b, v106
	v_exp_f32_e32 v106, v106
	s_nop 0
	v_add_f32_e32 v106, v106, v110
	v_cndmask_b32_e32 v106, v107, v106, vcc
	v_bitop3_b32 v107, v143, 56, v113 bitop3:0x48
	v_mul_f32_e32 v106, v106, v108
	v_lshl_add_u32 v107, v107, 1, 0
	v_cvt_pk_bf16_f32 v106, v106, s0
	v_add3_u32 v107, v107, v144, v137
	ds_write_b16 v107, v106 offset:16384
	v_sub_u32_e32 v106, v126, v113
	v_cvt_f32_u32_e32 v107, v106
	v_cmp_lt_i32_e32 vcc, -1, v106
	v_or_b32_e32 v110, 19, v132
	v_mul_f32_e32 v107, v107, v131
	v_mul_f32_e32 v107, 0xbfb8aa3b, v107
	v_exp_f32_e32 v107, v107
	s_nop 0
	v_add_f32_e32 v107, 0, v107
	v_cndmask_b32_e32 v108, 0, v107, vcc
	v_cmp_gt_i32_e32 vcc, 1, v106
	v_sub_u32_e32 v106, 0, v106
	v_cvt_f32_u32_e32 v106, v106
	v_mul_f32_e32 v106, v106, v130
	v_mul_f32_e32 v106, 0xbfb8aa3b, v106
	v_exp_f32_e32 v106, v106
	s_nop 0
	v_add_f32_e32 v106, v106, v108
	v_cndmask_b32_e32 v106, v107, v106, vcc
	v_bitop3_b32 v107, v129, 56, v113 bitop3:0x48
	v_mul_f32_e32 v106, v106, v109
	v_lshl_add_u32 v107, v107, 1, 0
	v_cvt_pk_bf16_f32 v106, v106, s0
	v_add3_u32 v107, v107, v145, v137
	ds_write_b16 v107, v106 offset:16384
	v_or_b32_e32 v106, 0x60, v0
	v_sub_u32_e32 v107, v132, v106
	v_cvt_f32_u32_e32 v108, v107
	v_cmp_lt_i32_e32 vcc, -1, v107
	v_mul_f32_e32 v108, v108, v131
	v_mul_f32_e32 v108, 0xbfb8aa3b, v108
	v_exp_f32_e32 v108, v108
	s_nop 0
	v_add_f32_e32 v108, 0, v108
	v_cndmask_b32_e32 v109, 0, v108, vcc
	v_cmp_gt_i32_e32 vcc, 1, v107
	v_sub_u32_e32 v107, 0, v107
	v_cvt_f32_u32_e32 v107, v107
	v_mul_f32_e32 v107, v107, v130
	v_mul_f32_e32 v107, 0xbfb8aa3b, v107
	v_exp_f32_e32 v107, v107
	s_nop 0
	v_add_f32_e32 v107, v107, v109
	v_cndmask_b32_e32 v107, v108, v107, vcc
	v_mul_f32_e32 v102, v107, v102
	v_bitop3_b32 v107, v139, 56, v106 bitop3:0x48
	v_lshl_add_u32 v107, v107, 1, 0
	v_cvt_pk_bf16_f32 v102, v102, s0
	v_add3_u32 v107, v107, v140, v137
	ds_write_b16 v107, v102 offset:16384
	v_sub_u32_e32 v102, v133, v106
	v_cvt_f32_u32_e32 v107, v102
	v_cmp_lt_i32_e32 vcc, -1, v102
	v_mul_f32_e32 v107, v107, v131
	v_mul_f32_e32 v107, 0xbfb8aa3b, v107
	v_exp_f32_e32 v107, v107
	s_nop 0
	v_add_f32_e32 v107, 0, v107
	v_cndmask_b32_e32 v108, 0, v107, vcc
	v_cmp_gt_i32_e32 vcc, 1, v102
	v_sub_u32_e32 v102, 0, v102
	v_cvt_f32_u32_e32 v102, v102
	v_mul_f32_e32 v102, v102, v130
	v_mul_f32_e32 v102, 0xbfb8aa3b, v102
	v_exp_f32_e32 v102, v102
	s_nop 0
	v_add_f32_e32 v102, v102, v108
	v_cndmask_b32_e32 v102, v107, v102, vcc
	v_mul_f32_e32 v102, v102, v103
	v_bitop3_b32 v103, v141, 56, v106 bitop3:0x48
	v_lshl_add_u32 v103, v103, 1, 0
	v_cvt_pk_bf16_f32 v102, v102, s0
	v_add3_u32 v103, v103, v142, v137
	ds_write_b16 v103, v102 offset:16384
	v_sub_u32_e32 v102, v127, v106
	v_cvt_f32_u32_e32 v103, v102
	v_cmp_lt_i32_e32 vcc, -1, v102
	v_mul_f32_e32 v103, v103, v131
	v_mul_f32_e32 v103, 0xbfb8aa3b, v103
	v_exp_f32_e32 v103, v103
	s_nop 0
	v_add_f32_e32 v103, 0, v103
	v_cndmask_b32_e32 v107, 0, v103, vcc
	v_cmp_gt_i32_e32 vcc, 1, v102
	v_sub_u32_e32 v102, 0, v102
	v_cvt_f32_u32_e32 v102, v102
	v_mul_f32_e32 v102, v102, v130
	v_mul_f32_e32 v102, 0xbfb8aa3b, v102
	v_exp_f32_e32 v102, v102
	s_nop 0
	v_add_f32_e32 v102, v102, v107
	v_cndmask_b32_e32 v102, v103, v102, vcc
	v_bitop3_b32 v103, v143, 56, v106 bitop3:0x48
	v_mul_f32_e32 v102, v102, v104
	v_lshl_add_u32 v103, v103, 1, 0
	v_cvt_pk_bf16_f32 v102, v102, s0
	v_add3_u32 v103, v103, v144, v137
	ds_write_b16 v103, v102 offset:16384
	v_sub_u32_e32 v102, v126, v106
	v_cvt_f32_u32_e32 v103, v102
	v_cmp_lt_i32_e32 vcc, -1, v102
	v_mul_f32_e32 v103, v103, v131
	v_mul_f32_e32 v103, 0xbfb8aa3b, v103
	v_exp_f32_e32 v103, v103
	s_nop 0
	v_add_f32_e32 v103, 0, v103
	v_cndmask_b32_e32 v104, 0, v103, vcc
	v_cmp_gt_i32_e32 vcc, 1, v102
	v_sub_u32_e32 v102, 0, v102
	v_cvt_f32_u32_e32 v102, v102
	v_mul_f32_e32 v102, v102, v130
	v_mul_f32_e32 v102, 0xbfb8aa3b, v102
	v_exp_f32_e32 v102, v102
	s_nop 0
	v_add_f32_e32 v102, v102, v104
	v_cndmask_b32_e32 v102, v103, v102, vcc
	v_bitop3_b32 v103, v129, 56, v106 bitop3:0x48
	v_mul_f32_e32 v102, v102, v105
	v_lshl_add_u32 v103, v103, 1, 0
	v_cvt_pk_bf16_f32 v102, v102, s0
	v_add3_u32 v103, v103, v145, v137
	ds_write_b16 v103, v102 offset:16384
	v_or_b32_e32 v102, 0x70, v0
	v_sub_u32_e32 v103, v132, v102
	v_cvt_f32_u32_e32 v104, v103
	v_cmp_lt_i32_e32 vcc, -1, v103
	v_mul_f32_e32 v104, v104, v131
	v_mul_f32_e32 v104, 0xbfb8aa3b, v104
	v_exp_f32_e32 v104, v104
	s_nop 0
	v_add_f32_e32 v104, 0, v104
	v_cndmask_b32_e32 v105, 0, v104, vcc
	v_cmp_gt_i32_e32 vcc, 1, v103
	v_sub_u32_e32 v103, 0, v103
	v_cvt_f32_u32_e32 v103, v103
	v_mul_f32_e32 v103, v103, v130
	v_mul_f32_e32 v103, 0xbfb8aa3b, v103
	v_exp_f32_e32 v103, v103
	s_nop 0
	v_add_f32_e32 v103, v103, v105
	v_cndmask_b32_e32 v103, v104, v103, vcc
	v_mul_f32_e32 v98, v103, v98
	v_bitop3_b32 v103, v139, 56, v102 bitop3:0x48
	v_lshl_add_u32 v103, v103, 1, 0
	v_cvt_pk_bf16_f32 v98, v98, s0
	v_add3_u32 v103, v103, v140, v137
	ds_write_b16 v103, v98 offset:16384
	v_sub_u32_e32 v98, v133, v102
	v_cvt_f32_u32_e32 v103, v98
	v_cmp_lt_i32_e32 vcc, -1, v98
	v_mul_f32_e32 v103, v103, v131
	v_mul_f32_e32 v103, 0xbfb8aa3b, v103
	v_exp_f32_e32 v103, v103
	s_nop 0
	v_add_f32_e32 v103, 0, v103
	v_cndmask_b32_e32 v104, 0, v103, vcc
	v_cmp_gt_i32_e32 vcc, 1, v98
	v_sub_u32_e32 v98, 0, v98
	v_cvt_f32_u32_e32 v98, v98
	v_mul_f32_e32 v98, v98, v130
	v_mul_f32_e32 v98, 0xbfb8aa3b, v98
	v_exp_f32_e32 v98, v98
	s_nop 0
	v_add_f32_e32 v98, v98, v104
	v_cndmask_b32_e32 v98, v103, v98, vcc
	v_mul_f32_e32 v98, v98, v99
	v_bitop3_b32 v99, v141, 56, v102 bitop3:0x48
	v_lshl_add_u32 v99, v99, 1, 0
	v_cvt_pk_bf16_f32 v98, v98, s0
	v_add3_u32 v99, v99, v142, v137
	ds_write_b16 v99, v98 offset:16384
	v_sub_u32_e32 v98, v127, v102
	v_cvt_f32_u32_e32 v99, v98
	v_cmp_lt_i32_e32 vcc, -1, v98
	v_mul_f32_e32 v99, v99, v131
	v_mul_f32_e32 v99, 0xbfb8aa3b, v99
	v_exp_f32_e32 v99, v99
	s_nop 0
	v_add_f32_e32 v99, 0, v99
	v_cndmask_b32_e32 v103, 0, v99, vcc
	v_cmp_gt_i32_e32 vcc, 1, v98
	v_sub_u32_e32 v98, 0, v98
	v_cvt_f32_u32_e32 v98, v98
	v_mul_f32_e32 v98, v98, v130
	v_mul_f32_e32 v98, 0xbfb8aa3b, v98
	v_exp_f32_e32 v98, v98
	s_nop 0
	v_add_f32_e32 v98, v98, v103
	v_cndmask_b32_e32 v98, v99, v98, vcc
	v_bitop3_b32 v99, v143, 56, v102 bitop3:0x48
	v_mul_f32_e32 v98, v98, v100
	v_lshl_add_u32 v99, v99, 1, 0
	v_cvt_pk_bf16_f32 v98, v98, s0
	v_add3_u32 v99, v99, v144, v137
	ds_write_b16 v99, v98 offset:16384
	v_sub_u32_e32 v98, v126, v102
	v_cvt_f32_u32_e32 v99, v98
	v_cmp_lt_i32_e32 vcc, -1, v98
	v_mul_f32_e32 v99, v99, v131
	v_mul_f32_e32 v99, 0xbfb8aa3b, v99
	v_exp_f32_e32 v99, v99
	s_nop 0
	v_add_f32_e32 v99, 0, v99
	v_cndmask_b32_e32 v100, 0, v99, vcc
	v_cmp_gt_i32_e32 vcc, 1, v98
	v_sub_u32_e32 v98, 0, v98
	v_cvt_f32_u32_e32 v98, v98
	v_mul_f32_e32 v98, v98, v130
	v_mul_f32_e32 v98, 0xbfb8aa3b, v98
	v_exp_f32_e32 v98, v98
	s_nop 0
	v_add_f32_e32 v98, v98, v100
	v_cndmask_b32_e32 v98, v99, v98, vcc
	v_bitop3_b32 v99, v129, 56, v102 bitop3:0x48
	v_mul_f32_e32 v98, v98, v101
	v_lshl_add_u32 v99, v99, 1, 0
	v_cvt_pk_bf16_f32 v98, v98, s0
	v_add3_u32 v99, v99, v145, v137
	ds_write_b16 v99, v98 offset:16384
	v_sub_u32_e32 v98, v115, v0
	v_cvt_f32_u32_e32 v99, v98
	v_cmp_lt_i32_e32 vcc, -1, v98
	v_mul_f32_e32 v99, v99, v131
	v_mul_f32_e32 v99, 0xbfb8aa3b, v99
	v_exp_f32_e32 v99, v99
	s_nop 0
	v_add_f32_e32 v99, 0, v99
	v_cndmask_b32_e32 v100, 0, v99, vcc
	v_cmp_gt_i32_e32 vcc, 1, v98
	v_sub_u32_e32 v98, 0, v98
	v_cvt_f32_u32_e32 v98, v98
	v_mul_f32_e32 v98, v98, v130
	v_mul_f32_e32 v98, 0xbfb8aa3b, v98
	v_exp_f32_e32 v98, v98
	s_nop 0
	v_add_f32_e32 v98, v98, v100
	v_cndmask_b32_e32 v98, v99, v98, vcc
	v_mul_f32_e32 v94, v98, v94
	v_cvt_pk_bf16_f32 v99, v94, s0
	v_lshlrev_b32_e32 v94, 2, v115
	v_bitop3_b32 v98, v94, 56, v0 bitop3:0xc8
	v_lshl_add_u32 v100, v98, 1, 0
	v_lshlrev_b32_e32 v98, 7, v115
	v_add3_u32 v103, v100, v98, v137
	ds_write_b16 v103, v99
	v_sub_u32_e32 v99, v112, v0
	v_cvt_f32_u32_e32 v100, v99
	v_cmp_lt_i32_e32 vcc, -1, v99
	v_mul_f32_e32 v100, v100, v131
	v_mul_f32_e32 v100, 0xbfb8aa3b, v100
	v_exp_f32_e32 v100, v100
	s_nop 0
	v_add_f32_e32 v100, 0, v100
	v_cndmask_b32_e32 v101, 0, v100, vcc
	v_cmp_gt_i32_e32 vcc, 1, v99
	v_sub_u32_e32 v99, 0, v99
	v_cvt_f32_u32_e32 v99, v99
	v_mul_f32_e32 v99, v99, v130
	v_mul_f32_e32 v99, 0xbfb8aa3b, v99
	v_exp_f32_e32 v99, v99
	s_nop 0
	v_add_f32_e32 v99, v99, v101
	v_cndmask_b32_e32 v99, v100, v99, vcc
	v_mul_f32_e32 v95, v99, v95
	v_cvt_pk_bf16_f32 v100, v95, s0
	v_lshlrev_b32_e32 v95, 2, v112
	v_bitop3_b32 v99, v95, 56, v0 bitop3:0xc8
	v_lshl_add_u32 v101, v99, 1, 0
	v_lshlrev_b32_e32 v99, 7, v112
	v_add3_u32 v104, v101, v99, v137
	ds_write_b16 v104, v100
	v_sub_u32_e32 v100, v111, v0
	v_cvt_f32_u32_e32 v101, v100
	v_cmp_lt_i32_e32 vcc, -1, v100
	v_mul_f32_e32 v101, v101, v131
	v_mul_f32_e32 v101, 0xbfb8aa3b, v101
	v_exp_f32_e32 v101, v101
	s_nop 0
	v_add_f32_e32 v101, 0, v101
	v_cndmask_b32_e32 v105, 0, v101, vcc
	v_cmp_gt_i32_e32 vcc, 1, v100
	v_sub_u32_e32 v100, 0, v100
	v_cvt_f32_u32_e32 v100, v100
	v_mul_f32_e32 v100, v100, v130
	v_mul_f32_e32 v100, 0xbfb8aa3b, v100
	v_exp_f32_e32 v100, v100
	s_nop 0
	v_add_f32_e32 v100, v100, v105
	v_cndmask_b32_e32 v100, v101, v100, vcc
	v_mul_f32_e32 v96, v100, v96
	v_cvt_pk_bf16_f32 v101, v96, s0
	v_lshlrev_b32_e32 v96, 2, v111
	v_bitop3_b32 v100, v96, 56, v0 bitop3:0x48
	v_lshl_add_u32 v105, v100, 1, 0
	v_lshlrev_b32_e32 v100, 7, v111
	v_add3_u32 v105, v105, v100, v137
	ds_write_b16 v105, v101
	v_sub_u32_e32 v101, v110, v0
	v_cvt_f32_u32_e32 v107, v101
	v_cmp_lt_i32_e32 vcc, -1, v101
	v_mul_f32_e32 v107, v107, v131
	v_mul_f32_e32 v107, 0xbfb8aa3b, v107
	v_exp_f32_e32 v107, v107
	s_nop 0
	v_add_f32_e32 v107, 0, v107
	v_cndmask_b32_e32 v108, 0, v107, vcc
	v_cmp_gt_i32_e32 vcc, 1, v101
	v_sub_u32_e32 v101, 0, v101
	v_cvt_f32_u32_e32 v101, v101
	v_mul_f32_e32 v101, v101, v130
	v_mul_f32_e32 v101, 0xbfb8aa3b, v101
	v_exp_f32_e32 v101, v101
	s_nop 0
	v_add_f32_e32 v101, v101, v108
	v_cndmask_b32_e32 v101, v107, v101, vcc
	v_mul_f32_e32 v97, v101, v97
	v_cvt_pk_bf16_f32 v108, v97, s0
	v_lshlrev_b32_e32 v97, 2, v110
	v_bitop3_b32 v101, v97, 56, v0 bitop3:0x48
	v_lshl_add_u32 v107, v101, 1, 0
	v_lshlrev_b32_e32 v101, 7, v110
	v_add3_u32 v107, v107, v101, v137
	ds_write_b16 v107, v108
	v_bitop3_b32 v108, v94, 56, v128 bitop3:0x48
	v_lshl_add_u32 v108, v108, 1, 0
	v_add3_u32 v108, v108, v98, v137
	ds_write_b16 v108, v90
	v_sub_u32_e32 v90, v112, v128
	v_cvt_f32_u32_e32 v108, v90
	v_cmp_lt_i32_e32 vcc, -1, v90
	v_lshlrev_b32_e32 v0, 1, v0
	v_mul_f32_e32 v108, v108, v131
	v_mul_f32_e32 v108, 0xbfb8aa3b, v108
	v_exp_f32_e32 v108, v108
	s_nop 0
	v_add_f32_e32 v108, 0, v108
	v_cndmask_b32_e32 v109, 0, v108, vcc
	v_cmp_gt_i32_e32 vcc, 1, v90
	v_sub_u32_e32 v90, 0, v90
	v_cvt_f32_u32_e32 v90, v90
	v_mul_f32_e32 v90, v90, v130
	v_mul_f32_e32 v90, 0xbfb8aa3b, v90
	v_exp_f32_e32 v90, v90
	s_nop 0
	v_add_f32_e32 v90, v90, v109
	v_cndmask_b32_e32 v90, v108, v90, vcc
	v_mul_f32_e32 v90, v90, v91
	v_bitop3_b32 v91, v95, 56, v128 bitop3:0x48
	v_lshl_add_u32 v91, v91, 1, 0
	v_cvt_pk_bf16_f32 v90, v90, s0
	v_add3_u32 v91, v91, v99, v137
	ds_write_b16 v91, v90
	v_sub_u32_e32 v90, v111, v128
	v_cvt_f32_u32_e32 v91, v90
	v_cmp_lt_i32_e32 vcc, -1, v90
	v_mul_f32_e32 v91, v91, v131
	v_mul_f32_e32 v91, 0xbfb8aa3b, v91
	v_exp_f32_e32 v91, v91
	s_nop 0
	v_add_f32_e32 v91, 0, v91
	v_cndmask_b32_e32 v108, 0, v91, vcc
	v_cmp_gt_i32_e32 vcc, 1, v90
	v_sub_u32_e32 v90, 0, v90
	v_cvt_f32_u32_e32 v90, v90
	v_mul_f32_e32 v90, v90, v130
	v_mul_f32_e32 v90, 0xbfb8aa3b, v90
	v_exp_f32_e32 v90, v90
	s_nop 0
	v_add_f32_e32 v90, v90, v108
	v_cndmask_b32_e32 v90, v91, v90, vcc
	v_bitop3_b32 v91, v96, 56, v128 bitop3:0x48
	v_mul_f32_e32 v90, v90, v92
	v_lshl_add_u32 v91, v91, 1, 0
	v_cvt_pk_bf16_f32 v90, v90, s0
	v_add3_u32 v91, v91, v100, v137
	ds_write_b16 v91, v90
	v_sub_u32_e32 v90, v110, v128
	v_cvt_f32_u32_e32 v91, v90
	v_cmp_lt_i32_e32 vcc, -1, v90
	v_mul_f32_e32 v91, v91, v131
	v_mul_f32_e32 v91, 0xbfb8aa3b, v91
	v_exp_f32_e32 v91, v91
	s_nop 0
	v_add_f32_e32 v91, 0, v91
	v_cndmask_b32_e32 v92, 0, v91, vcc
	v_cmp_gt_i32_e32 vcc, 1, v90
	v_sub_u32_e32 v90, 0, v90
	v_cvt_f32_u32_e32 v90, v90
	v_mul_f32_e32 v90, v90, v130
	v_mul_f32_e32 v90, 0xbfb8aa3b, v90
	v_exp_f32_e32 v90, v90
	s_nop 0
	v_add_f32_e32 v90, v90, v92
	v_cndmask_b32_e32 v90, v91, v90, vcc
	v_bitop3_b32 v91, v97, 56, v128 bitop3:0x48
	v_mul_f32_e32 v90, v90, v93
	v_lshl_add_u32 v91, v91, 1, 0
	v_cvt_pk_bf16_f32 v90, v90, s0
	v_add3_u32 v91, v91, v101, v137
	ds_write_b16 v91, v90
	v_sub_u32_e32 v90, v115, v122
	v_cvt_f32_u32_e32 v91, v90
	v_cmp_lt_i32_e32 vcc, -1, v90
	v_mul_f32_e32 v91, v91, v131
	v_mul_f32_e32 v91, 0xbfb8aa3b, v91
	v_exp_f32_e32 v91, v91
	s_nop 0
	v_add_f32_e32 v91, 0, v91
	v_cndmask_b32_e32 v92, 0, v91, vcc
	v_cmp_gt_i32_e32 vcc, 1, v90
	v_sub_u32_e32 v90, 0, v90
	v_cvt_f32_u32_e32 v90, v90
	v_mul_f32_e32 v90, v90, v130
	v_mul_f32_e32 v90, 0xbfb8aa3b, v90
	v_exp_f32_e32 v90, v90
	s_nop 0
	v_add_f32_e32 v90, v90, v92
	v_cndmask_b32_e32 v90, v91, v90, vcc
	v_mul_f32_e32 v86, v90, v86
	v_bitop3_b32 v90, v94, 56, v122 bitop3:0x48
	v_lshl_add_u32 v90, v90, 1, 0
	v_cvt_pk_bf16_f32 v86, v86, s0
	v_add3_u32 v90, v90, v98, v137
	ds_write_b16 v90, v86
	v_sub_u32_e32 v86, v112, v122
	v_cvt_f32_u32_e32 v90, v86
	v_cmp_lt_i32_e32 vcc, -1, v86
	v_mul_f32_e32 v90, v90, v131
	v_mul_f32_e32 v90, 0xbfb8aa3b, v90
	v_exp_f32_e32 v90, v90
	s_nop 0
	v_add_f32_e32 v90, 0, v90
	v_cndmask_b32_e32 v91, 0, v90, vcc
	v_cmp_gt_i32_e32 vcc, 1, v86
	v_sub_u32_e32 v86, 0, v86
	v_cvt_f32_u32_e32 v86, v86
	v_mul_f32_e32 v86, v86, v130
	v_mul_f32_e32 v86, 0xbfb8aa3b, v86
	v_exp_f32_e32 v86, v86
	s_nop 0
	v_add_f32_e32 v86, v86, v91
	v_cndmask_b32_e32 v86, v90, v86, vcc
	v_mul_f32_e32 v86, v86, v87
	v_bitop3_b32 v87, v95, 56, v122 bitop3:0x48
	v_lshl_add_u32 v87, v87, 1, 0
	v_cvt_pk_bf16_f32 v86, v86, s0
	v_add3_u32 v87, v87, v99, v137
	ds_write_b16 v87, v86
	v_sub_u32_e32 v86, v111, v122
	v_cvt_f32_u32_e32 v87, v86
	v_cmp_lt_i32_e32 vcc, -1, v86
	v_mul_f32_e32 v87, v87, v131
	v_mul_f32_e32 v87, 0xbfb8aa3b, v87
	v_exp_f32_e32 v87, v87
	s_nop 0
	v_add_f32_e32 v87, 0, v87
	v_cndmask_b32_e32 v90, 0, v87, vcc
	v_cmp_gt_i32_e32 vcc, 1, v86
	v_sub_u32_e32 v86, 0, v86
	v_cvt_f32_u32_e32 v86, v86
	v_mul_f32_e32 v86, v86, v130
	v_mul_f32_e32 v86, 0xbfb8aa3b, v86
	v_exp_f32_e32 v86, v86
	s_nop 0
	v_add_f32_e32 v86, v86, v90
	v_cndmask_b32_e32 v86, v87, v86, vcc
	v_bitop3_b32 v87, v96, 56, v122 bitop3:0x48
	v_mul_f32_e32 v86, v86, v88
	v_lshl_add_u32 v87, v87, 1, 0
	v_cvt_pk_bf16_f32 v86, v86, s0
	v_add3_u32 v87, v87, v100, v137
	ds_write_b16 v87, v86
	v_sub_u32_e32 v86, v110, v122
	v_cvt_f32_u32_e32 v87, v86
	v_cmp_lt_i32_e32 vcc, -1, v86
	v_mul_f32_e32 v87, v87, v131
	v_mul_f32_e32 v87, 0xbfb8aa3b, v87
	v_exp_f32_e32 v87, v87
	s_nop 0
	v_add_f32_e32 v87, 0, v87
	v_cndmask_b32_e32 v88, 0, v87, vcc
	v_cmp_gt_i32_e32 vcc, 1, v86
	v_sub_u32_e32 v86, 0, v86
	v_cvt_f32_u32_e32 v86, v86
	v_mul_f32_e32 v86, v86, v130
	v_mul_f32_e32 v86, 0xbfb8aa3b, v86
	v_exp_f32_e32 v86, v86
	s_nop 0
	v_add_f32_e32 v86, v86, v88
	v_cndmask_b32_e32 v86, v87, v86, vcc
	v_bitop3_b32 v87, v97, 56, v122 bitop3:0x48
	v_mul_f32_e32 v86, v86, v89
	v_lshl_add_u32 v87, v87, 1, 0
	v_cvt_pk_bf16_f32 v86, v86, s0
	v_add3_u32 v87, v87, v101, v137
	ds_write_b16 v87, v86
	v_sub_u32_e32 v86, v115, v118
	v_cvt_f32_u32_e32 v87, v86
	v_cmp_lt_i32_e32 vcc, -1, v86
	v_mul_f32_e32 v87, v87, v131
	v_mul_f32_e32 v87, 0xbfb8aa3b, v87
	v_exp_f32_e32 v87, v87
	s_nop 0
	v_add_f32_e32 v87, 0, v87
	v_cndmask_b32_e32 v88, 0, v87, vcc
	v_cmp_gt_i32_e32 vcc, 1, v86
	v_sub_u32_e32 v86, 0, v86
	v_cvt_f32_u32_e32 v86, v86
	v_mul_f32_e32 v86, v86, v130
	v_mul_f32_e32 v86, 0xbfb8aa3b, v86
	v_exp_f32_e32 v86, v86
	s_nop 0
	v_add_f32_e32 v86, v86, v88
	v_cndmask_b32_e32 v86, v87, v86, vcc
	v_mul_f32_e32 v82, v86, v82
	v_bitop3_b32 v86, v94, 56, v118 bitop3:0x48
	v_lshl_add_u32 v86, v86, 1, 0
	v_cvt_pk_bf16_f32 v82, v82, s0
	v_add3_u32 v86, v86, v98, v137
	ds_write_b16 v86, v82
	v_sub_u32_e32 v82, v112, v118
	v_cvt_f32_u32_e32 v86, v82
	v_cmp_lt_i32_e32 vcc, -1, v82
	v_mul_f32_e32 v86, v86, v131
	v_mul_f32_e32 v86, 0xbfb8aa3b, v86
	v_exp_f32_e32 v86, v86
	s_nop 0
	v_add_f32_e32 v86, 0, v86
	v_cndmask_b32_e32 v87, 0, v86, vcc
	v_cmp_gt_i32_e32 vcc, 1, v82
	v_sub_u32_e32 v82, 0, v82
	v_cvt_f32_u32_e32 v82, v82
	v_mul_f32_e32 v82, v82, v130
	v_mul_f32_e32 v82, 0xbfb8aa3b, v82
	v_exp_f32_e32 v82, v82
	s_nop 0
	v_add_f32_e32 v82, v82, v87
	v_cndmask_b32_e32 v82, v86, v82, vcc
	v_mul_f32_e32 v82, v82, v83
	v_bitop3_b32 v83, v95, 56, v118 bitop3:0x48
	v_lshl_add_u32 v83, v83, 1, 0
	v_cvt_pk_bf16_f32 v82, v82, s0
	v_add3_u32 v83, v83, v99, v137
	ds_write_b16 v83, v82
	v_sub_u32_e32 v82, v111, v118
	v_cvt_f32_u32_e32 v83, v82
	v_cmp_lt_i32_e32 vcc, -1, v82
	v_mul_f32_e32 v83, v83, v131
	v_mul_f32_e32 v83, 0xbfb8aa3b, v83
	v_exp_f32_e32 v83, v83
	s_nop 0
	v_add_f32_e32 v83, 0, v83
	v_cndmask_b32_e32 v86, 0, v83, vcc
	v_cmp_gt_i32_e32 vcc, 1, v82
	v_sub_u32_e32 v82, 0, v82
	v_cvt_f32_u32_e32 v82, v82
	v_mul_f32_e32 v82, v82, v130
	v_mul_f32_e32 v82, 0xbfb8aa3b, v82
	v_exp_f32_e32 v82, v82
	s_nop 0
	v_add_f32_e32 v82, v82, v86
	v_cndmask_b32_e32 v82, v83, v82, vcc
	v_bitop3_b32 v83, v96, 56, v118 bitop3:0x48
	v_mul_f32_e32 v82, v82, v84
	v_lshl_add_u32 v83, v83, 1, 0
	v_cvt_pk_bf16_f32 v82, v82, s0
	v_add3_u32 v83, v83, v100, v137
	ds_write_b16 v83, v82
	v_sub_u32_e32 v82, v110, v118
	v_cvt_f32_u32_e32 v83, v82
	v_cmp_lt_i32_e32 vcc, -1, v82
	v_mul_f32_e32 v83, v83, v131
	v_mul_f32_e32 v83, 0xbfb8aa3b, v83
	v_exp_f32_e32 v83, v83
	s_nop 0
	v_add_f32_e32 v83, 0, v83
	v_cndmask_b32_e32 v84, 0, v83, vcc
	v_cmp_gt_i32_e32 vcc, 1, v82
	v_sub_u32_e32 v82, 0, v82
	v_cvt_f32_u32_e32 v82, v82
	v_mul_f32_e32 v82, v82, v130
	v_mul_f32_e32 v82, 0xbfb8aa3b, v82
	v_exp_f32_e32 v82, v82
	s_nop 0
	v_add_f32_e32 v82, v82, v84
	v_cndmask_b32_e32 v82, v83, v82, vcc
	v_bitop3_b32 v83, v97, 56, v118 bitop3:0x48
	v_mul_f32_e32 v82, v82, v85
	v_lshl_add_u32 v83, v83, 1, 0
	v_cvt_pk_bf16_f32 v82, v82, s0
	v_add3_u32 v83, v83, v101, v137
	ds_write_b16 v83, v82
	v_sub_u32_e32 v82, v115, v114
	v_cvt_f32_u32_e32 v83, v82
	v_cmp_lt_i32_e32 vcc, -1, v82
	v_mul_f32_e32 v83, v83, v131
	v_mul_f32_e32 v83, 0xbfb8aa3b, v83
	v_exp_f32_e32 v83, v83
	s_nop 0
	v_add_f32_e32 v83, 0, v83
	v_cndmask_b32_e32 v84, 0, v83, vcc
	v_cmp_gt_i32_e32 vcc, 1, v82
	v_sub_u32_e32 v82, 0, v82
	v_cvt_f32_u32_e32 v82, v82
	v_mul_f32_e32 v82, v82, v130
	v_mul_f32_e32 v82, 0xbfb8aa3b, v82
	v_exp_f32_e32 v82, v82
	s_nop 0
	v_add_f32_e32 v82, v82, v84
	v_cndmask_b32_e32 v82, v83, v82, vcc
	v_mul_f32_e32 v78, v82, v78
	v_cvt_pk_bf16_f32 v78, v78, s0
	ds_write_b16 v103, v78 offset:16384
	v_sub_u32_e32 v78, v112, v114
	v_cvt_f32_u32_e32 v82, v78
	v_cmp_lt_i32_e32 vcc, -1, v78
	v_mul_f32_e32 v82, v82, v131
	v_mul_f32_e32 v82, 0xbfb8aa3b, v82
	v_exp_f32_e32 v82, v82
	s_nop 0
	v_add_f32_e32 v82, 0, v82
	v_cndmask_b32_e32 v83, 0, v82, vcc
	v_cmp_gt_i32_e32 vcc, 1, v78
	v_sub_u32_e32 v78, 0, v78
	v_cvt_f32_u32_e32 v78, v78
	v_mul_f32_e32 v78, v78, v130
	v_mul_f32_e32 v78, 0xbfb8aa3b, v78
	v_exp_f32_e32 v78, v78
	s_nop 0
	v_add_f32_e32 v78, v78, v83
	v_cndmask_b32_e32 v78, v82, v78, vcc
	v_mul_f32_e32 v78, v78, v79
	v_cvt_pk_bf16_f32 v78, v78, s0
	ds_write_b16 v104, v78 offset:16384
	v_sub_u32_e32 v78, v111, v114
	v_cvt_f32_u32_e32 v79, v78
	v_cmp_lt_i32_e32 vcc, -1, v78
	v_mul_f32_e32 v79, v79, v131
	v_mul_f32_e32 v79, 0xbfb8aa3b, v79
	v_exp_f32_e32 v79, v79
	s_nop 0
	v_add_f32_e32 v79, 0, v79
	v_cndmask_b32_e32 v82, 0, v79, vcc
	v_cmp_gt_i32_e32 vcc, 1, v78
	v_sub_u32_e32 v78, 0, v78
	v_cvt_f32_u32_e32 v78, v78
	v_mul_f32_e32 v78, v78, v130
	v_mul_f32_e32 v78, 0xbfb8aa3b, v78
	v_exp_f32_e32 v78, v78
	s_nop 0
	v_add_f32_e32 v78, v78, v82
	v_cndmask_b32_e32 v78, v79, v78, vcc
	v_mul_f32_e32 v78, v78, v80
	v_cvt_pk_bf16_f32 v78, v78, s0
	ds_write_b16 v105, v78 offset:16384
	v_sub_u32_e32 v78, v110, v114
	v_cvt_f32_u32_e32 v79, v78
	v_cmp_lt_i32_e32 vcc, -1, v78
	v_mul_f32_e32 v79, v79, v131
	v_mul_f32_e32 v79, 0xbfb8aa3b, v79
	v_exp_f32_e32 v79, v79
	s_nop 0
	v_add_f32_e32 v79, 0, v79
	v_cndmask_b32_e32 v80, 0, v79, vcc
	v_cmp_gt_i32_e32 vcc, 1, v78
	v_sub_u32_e32 v78, 0, v78
	v_cvt_f32_u32_e32 v78, v78
	v_mul_f32_e32 v78, v78, v130
	v_mul_f32_e32 v78, 0xbfb8aa3b, v78
	v_exp_f32_e32 v78, v78
	s_nop 0
	v_add_f32_e32 v78, v78, v80
	v_cndmask_b32_e32 v78, v79, v78, vcc
	v_mul_f32_e32 v78, v78, v81
	v_cvt_pk_bf16_f32 v78, v78, s0
	ds_write_b16 v107, v78 offset:16384
	v_sub_u32_e32 v78, v115, v113
	v_cvt_f32_u32_e32 v79, v78
	v_cmp_lt_i32_e32 vcc, -1, v78
	v_mul_f32_e32 v79, v79, v131
	v_mul_f32_e32 v79, 0xbfb8aa3b, v79
	v_exp_f32_e32 v79, v79
	s_nop 0
	v_add_f32_e32 v79, 0, v79
	v_cndmask_b32_e32 v80, 0, v79, vcc
	v_cmp_gt_i32_e32 vcc, 1, v78
	v_sub_u32_e32 v78, 0, v78
	v_cvt_f32_u32_e32 v78, v78
	v_mul_f32_e32 v78, v78, v130
	v_mul_f32_e32 v78, 0xbfb8aa3b, v78
	v_exp_f32_e32 v78, v78
	s_nop 0
	v_add_f32_e32 v78, v78, v80
	v_cndmask_b32_e32 v78, v79, v78, vcc
	v_mul_f32_e32 v74, v78, v74
	v_bitop3_b32 v78, v94, 56, v113 bitop3:0x48
	v_lshl_add_u32 v78, v78, 1, 0
	v_cvt_pk_bf16_f32 v74, v74, s0
	v_add3_u32 v78, v78, v98, v137
	ds_write_b16 v78, v74 offset:16384
	v_sub_u32_e32 v74, v112, v113
	v_cvt_f32_u32_e32 v78, v74
	v_cmp_lt_i32_e32 vcc, -1, v74
	v_mul_f32_e32 v78, v78, v131
	v_mul_f32_e32 v78, 0xbfb8aa3b, v78
	v_exp_f32_e32 v78, v78
	s_nop 0
	v_add_f32_e32 v78, 0, v78
	v_cndmask_b32_e32 v79, 0, v78, vcc
	v_cmp_gt_i32_e32 vcc, 1, v74
	v_sub_u32_e32 v74, 0, v74
	v_cvt_f32_u32_e32 v74, v74
	v_mul_f32_e32 v74, v74, v130
	v_mul_f32_e32 v74, 0xbfb8aa3b, v74
	v_exp_f32_e32 v74, v74
	s_nop 0
	v_add_f32_e32 v74, v74, v79
	v_cndmask_b32_e32 v74, v78, v74, vcc
	v_mul_f32_e32 v74, v74, v75
	v_bitop3_b32 v75, v95, 56, v113 bitop3:0x48
	v_lshl_add_u32 v75, v75, 1, 0
	v_cvt_pk_bf16_f32 v74, v74, s0
	v_add3_u32 v75, v75, v99, v137
	ds_write_b16 v75, v74 offset:16384
	v_sub_u32_e32 v74, v111, v113
	v_cvt_f32_u32_e32 v75, v74
	v_cmp_lt_i32_e32 vcc, -1, v74
	v_mul_f32_e32 v75, v75, v131
	v_mul_f32_e32 v75, 0xbfb8aa3b, v75
	v_exp_f32_e32 v75, v75
	s_nop 0
	v_add_f32_e32 v75, 0, v75
	v_cndmask_b32_e32 v78, 0, v75, vcc
	v_cmp_gt_i32_e32 vcc, 1, v74
	v_sub_u32_e32 v74, 0, v74
	v_cvt_f32_u32_e32 v74, v74
	v_mul_f32_e32 v74, v74, v130
	v_mul_f32_e32 v74, 0xbfb8aa3b, v74
	v_exp_f32_e32 v74, v74
	s_nop 0
	v_add_f32_e32 v74, v74, v78
	v_cndmask_b32_e32 v74, v75, v74, vcc
	v_bitop3_b32 v75, v96, 56, v113 bitop3:0x48
	v_mul_f32_e32 v74, v74, v76
	v_lshl_add_u32 v75, v75, 1, 0
	v_cvt_pk_bf16_f32 v74, v74, s0
	v_add3_u32 v75, v75, v100, v137
	ds_write_b16 v75, v74 offset:16384
	v_sub_u32_e32 v74, v110, v113
	v_cvt_f32_u32_e32 v75, v74
	v_cmp_lt_i32_e32 vcc, -1, v74
	v_mul_f32_e32 v75, v75, v131
	v_mul_f32_e32 v75, 0xbfb8aa3b, v75
	v_exp_f32_e32 v75, v75
	s_nop 0
	v_add_f32_e32 v75, 0, v75
	v_cndmask_b32_e32 v76, 0, v75, vcc
	v_cmp_gt_i32_e32 vcc, 1, v74
	v_sub_u32_e32 v74, 0, v74
	v_cvt_f32_u32_e32 v74, v74
	v_mul_f32_e32 v74, v74, v130
	v_mul_f32_e32 v74, 0xbfb8aa3b, v74
	v_exp_f32_e32 v74, v74
	s_nop 0
	v_add_f32_e32 v74, v74, v76
	v_cndmask_b32_e32 v74, v75, v74, vcc
	v_bitop3_b32 v75, v97, 56, v113 bitop3:0x48
	v_mul_f32_e32 v74, v74, v77
	v_lshl_add_u32 v75, v75, 1, 0
	v_cvt_pk_bf16_f32 v74, v74, s0
	v_add3_u32 v75, v75, v101, v137
	ds_write_b16 v75, v74 offset:16384
	v_sub_u32_e32 v74, v115, v106
	v_cvt_f32_u32_e32 v75, v74
	v_cmp_lt_i32_e32 vcc, -1, v74
	v_add3_u32 v113, 0, v135, v134
	v_add_u32_e32 v114, s0, v113
	v_mul_f32_e32 v75, v75, v131
	v_mul_f32_e32 v75, 0xbfb8aa3b, v75
	v_exp_f32_e32 v75, v75
	s_nop 0
	v_add_f32_e32 v75, 0, v75
	v_cndmask_b32_e32 v76, 0, v75, vcc
	v_cmp_gt_i32_e32 vcc, 1, v74
	v_sub_u32_e32 v74, 0, v74
	v_cvt_f32_u32_e32 v74, v74
	v_mul_f32_e32 v74, v74, v130
	v_mul_f32_e32 v74, 0xbfb8aa3b, v74
	v_exp_f32_e32 v74, v74
	s_nop 0
	v_add_f32_e32 v74, v74, v76
	v_cndmask_b32_e32 v74, v75, v74, vcc
	v_mul_f32_e32 v70, v74, v70
	v_bitop3_b32 v74, v94, 56, v106 bitop3:0x48
	v_lshl_add_u32 v74, v74, 1, 0
	v_cvt_pk_bf16_f32 v70, v70, s0
	v_add3_u32 v74, v74, v98, v137
	ds_write_b16 v74, v70 offset:16384
	v_sub_u32_e32 v70, v112, v106
	v_cvt_f32_u32_e32 v74, v70
	v_cmp_lt_i32_e32 vcc, -1, v70
	v_mul_f32_e32 v74, v74, v131
	v_mul_f32_e32 v74, 0xbfb8aa3b, v74
	v_exp_f32_e32 v74, v74
	s_nop 0
	v_add_f32_e32 v74, 0, v74
	v_cndmask_b32_e32 v75, 0, v74, vcc
	v_cmp_gt_i32_e32 vcc, 1, v70
	v_sub_u32_e32 v70, 0, v70
	v_cvt_f32_u32_e32 v70, v70
	v_mul_f32_e32 v70, v70, v130
	v_mul_f32_e32 v70, 0xbfb8aa3b, v70
	v_exp_f32_e32 v70, v70
	s_nop 0
	v_add_f32_e32 v70, v70, v75
	v_cndmask_b32_e32 v70, v74, v70, vcc
	v_mul_f32_e32 v70, v70, v71
	v_bitop3_b32 v71, v95, 56, v106 bitop3:0x48
	v_lshl_add_u32 v71, v71, 1, 0
	v_cvt_pk_bf16_f32 v70, v70, s0
	v_add3_u32 v71, v71, v99, v137
	ds_write_b16 v71, v70 offset:16384
	v_sub_u32_e32 v70, v111, v106
	v_cvt_f32_u32_e32 v71, v70
	v_cmp_lt_i32_e32 vcc, -1, v70
	v_mul_f32_e32 v71, v71, v131
	v_mul_f32_e32 v71, 0xbfb8aa3b, v71
	v_exp_f32_e32 v71, v71
	s_nop 0
	v_add_f32_e32 v71, 0, v71
	v_cndmask_b32_e32 v74, 0, v71, vcc
	v_cmp_gt_i32_e32 vcc, 1, v70
	v_sub_u32_e32 v70, 0, v70
	v_cvt_f32_u32_e32 v70, v70
	v_mul_f32_e32 v70, v70, v130
	v_mul_f32_e32 v70, 0xbfb8aa3b, v70
	v_exp_f32_e32 v70, v70
	s_nop 0
	v_add_f32_e32 v70, v70, v74
	v_cndmask_b32_e32 v70, v71, v70, vcc
	v_bitop3_b32 v71, v96, 56, v106 bitop3:0x48
	v_mul_f32_e32 v70, v70, v72
	v_lshl_add_u32 v71, v71, 1, 0
	v_cvt_pk_bf16_f32 v70, v70, s0
	v_add3_u32 v71, v71, v100, v137
	ds_write_b16 v71, v70 offset:16384
	v_sub_u32_e32 v70, v110, v106
	v_cvt_f32_u32_e32 v71, v70
	v_cmp_lt_i32_e32 vcc, -1, v70
	v_mul_f32_e32 v71, v71, v131
	v_mul_f32_e32 v71, 0xbfb8aa3b, v71
	v_exp_f32_e32 v71, v71
	s_nop 0
	v_add_f32_e32 v71, 0, v71
	v_cndmask_b32_e32 v72, 0, v71, vcc
	v_cmp_gt_i32_e32 vcc, 1, v70
	v_sub_u32_e32 v70, 0, v70
	v_cvt_f32_u32_e32 v70, v70
	v_mul_f32_e32 v70, v70, v130
	v_mul_f32_e32 v70, 0xbfb8aa3b, v70
	v_exp_f32_e32 v70, v70
	s_nop 0
	v_add_f32_e32 v70, v70, v72
	v_cndmask_b32_e32 v70, v71, v70, vcc
	v_bitop3_b32 v71, v97, 56, v106 bitop3:0x48
	v_mul_f32_e32 v70, v70, v73
	v_lshl_add_u32 v71, v71, 1, 0
	v_cvt_pk_bf16_f32 v70, v70, s0
	v_add3_u32 v71, v71, v101, v137
	ds_write_b16 v71, v70 offset:16384
	v_sub_u32_e32 v70, v115, v102
	v_cvt_f32_u32_e32 v71, v70
	v_cmp_lt_i32_e32 vcc, -1, v70
	v_mul_f32_e32 v71, v71, v131
	v_mul_f32_e32 v71, 0xbfb8aa3b, v71
	v_exp_f32_e32 v71, v71
	s_nop 0
	v_add_f32_e32 v71, 0, v71
	v_cndmask_b32_e32 v72, 0, v71, vcc
	v_cmp_gt_i32_e32 vcc, 1, v70
	v_sub_u32_e32 v70, 0, v70
	v_cvt_f32_u32_e32 v70, v70
	v_mul_f32_e32 v70, v70, v130
	v_mul_f32_e32 v70, 0xbfb8aa3b, v70
	v_exp_f32_e32 v70, v70
	s_nop 0
	v_add_f32_e32 v70, v70, v72
	v_cndmask_b32_e32 v70, v71, v70, vcc
	v_mul_f32_e32 v66, v70, v66
	v_bitop3_b32 v70, v94, 56, v102 bitop3:0x48
	v_lshl_add_u32 v70, v70, 1, 0
	v_cvt_pk_bf16_f32 v66, v66, s0
	v_add3_u32 v70, v70, v98, v137
	ds_write_b16 v70, v66 offset:16384
	v_sub_u32_e32 v66, v112, v102
	v_cvt_f32_u32_e32 v70, v66
	v_cmp_lt_i32_e32 vcc, -1, v66
	v_mul_f32_e32 v70, v70, v131
	v_mul_f32_e32 v70, 0xbfb8aa3b, v70
	v_exp_f32_e32 v70, v70
	s_nop 0
	v_add_f32_e32 v70, 0, v70
	v_cndmask_b32_e32 v71, 0, v70, vcc
	v_cmp_gt_i32_e32 vcc, 1, v66
	v_sub_u32_e32 v66, 0, v66
	v_cvt_f32_u32_e32 v66, v66
	v_mul_f32_e32 v66, v66, v130
	v_mul_f32_e32 v66, 0xbfb8aa3b, v66
	v_exp_f32_e32 v66, v66
	s_nop 0
	v_add_f32_e32 v66, v66, v71
	v_cndmask_b32_e32 v66, v70, v66, vcc
	v_mul_f32_e32 v66, v66, v67
	v_bitop3_b32 v67, v95, 56, v102 bitop3:0x48
	v_lshl_add_u32 v67, v67, 1, 0
	v_cvt_pk_bf16_f32 v66, v66, s0
	v_add3_u32 v67, v67, v99, v137
	ds_write_b16 v67, v66 offset:16384
	v_sub_u32_e32 v66, v111, v102
	v_cvt_f32_u32_e32 v67, v66
	v_cmp_lt_i32_e32 vcc, -1, v66
	v_mul_f32_e32 v67, v67, v131
	v_mul_f32_e32 v67, 0xbfb8aa3b, v67
	v_exp_f32_e32 v67, v67
	s_nop 0
	v_add_f32_e32 v67, 0, v67
	v_cndmask_b32_e32 v70, 0, v67, vcc
	v_cmp_gt_i32_e32 vcc, 1, v66
	v_sub_u32_e32 v66, 0, v66
	v_cvt_f32_u32_e32 v66, v66
	v_mul_f32_e32 v66, v66, v130
	v_mul_f32_e32 v66, 0xbfb8aa3b, v66
	v_exp_f32_e32 v66, v66
	s_nop 0
	v_add_f32_e32 v66, v66, v70
	v_cndmask_b32_e32 v66, v67, v66, vcc
	v_bitop3_b32 v67, v96, 56, v102 bitop3:0x48
	v_mul_f32_e32 v66, v66, v68
	v_lshl_add_u32 v67, v67, 1, 0
	v_cvt_pk_bf16_f32 v66, v66, s0
	v_add3_u32 v67, v67, v100, v137
	ds_write_b16 v67, v66 offset:16384
	v_sub_u32_e32 v66, v110, v102
	v_cvt_f32_u32_e32 v67, v66
	v_cmp_lt_i32_e32 vcc, -1, v66
	v_mul_f32_e32 v67, v67, v131
	v_mul_f32_e32 v67, 0xbfb8aa3b, v67
	v_exp_f32_e32 v67, v67
	s_nop 0
	v_add_f32_e32 v67, 0, v67
	v_cndmask_b32_e32 v68, 0, v67, vcc
	v_cmp_gt_i32_e32 vcc, 1, v66
	v_sub_u32_e32 v66, 0, v66
	v_cvt_f32_u32_e32 v66, v66
	v_mul_f32_e32 v66, v66, v130
	v_mul_f32_e32 v66, 0xbfb8aa3b, v66
	v_exp_f32_e32 v66, v66
	s_nop 0
	v_add_f32_e32 v66, v66, v68
	v_cndmask_b32_e32 v66, v67, v66, vcc
	v_bitop3_b32 v67, v97, 56, v102 bitop3:0x48
	v_mul_f32_e32 v66, v66, v69
	v_lshl_add_u32 v67, v67, 1, 0
	v_cvt_pk_bf16_f32 v66, v66, s0
	v_add3_u32 v67, v67, v101, v137
	ds_write_b16 v67, v66 offset:16384
	s_waitcnt lgkmcnt(0)
	s_barrier
	v_and_b32_e32 v232, 15, v207
	v_lshlrev_b32_e32 v232, 1, v232
	v_mov_b32_e32 v233, 0
	v_mov_b32_e32 v247, 0
	v_or_b32_e32 v246, 16, v132
	v_add_u32_e32 v246, s6, v246
	v_mul_u32_u24_e32 v246, 0x1200, v246
	v_lshl_add_u64 v[248:249], s[92:93], 0, v[246:247]
	v_lshl_add_u64 v[248:249], v[248:249], 0, s[26:27]
	v_lshl_add_u64 v[248:249], v[248:249], 0, v[232:233]
	v_lshl_add_u64 v[248:249], v[248:249], 0, s[10:11]
	global_load_ushort v176, v[248:249], off
	global_load_ushort v177, v[248:249], off offset:32
	global_load_ushort v178, v[248:249], off offset:64
	global_load_ushort v179, v[248:249], off offset:96
	v_or_b32_e32 v246, 17, v132
	v_add_u32_e32 v246, s6, v246
	v_mul_u32_u24_e32 v246, 0x1200, v246
	v_lshl_add_u64 v[248:249], s[92:93], 0, v[246:247]
	v_lshl_add_u64 v[248:249], v[248:249], 0, s[26:27]
	v_lshl_add_u64 v[248:249], v[248:249], 0, v[232:233]
	v_lshl_add_u64 v[248:249], v[248:249], 0, s[10:11]
	global_load_ushort v180, v[248:249], off
	global_load_ushort v181, v[248:249], off offset:32
	global_load_ushort v182, v[248:249], off offset:64
	global_load_ushort v183, v[248:249], off offset:96
	v_or_b32_e32 v246, 18, v132
	v_add_u32_e32 v246, s6, v246
	v_mul_u32_u24_e32 v246, 0x1200, v246
	v_lshl_add_u64 v[248:249], s[92:93], 0, v[246:247]
	v_lshl_add_u64 v[248:249], v[248:249], 0, s[26:27]
	v_lshl_add_u64 v[248:249], v[248:249], 0, v[232:233]
	v_lshl_add_u64 v[248:249], v[248:249], 0, s[10:11]
	global_load_ushort v184, v[248:249], off
	global_load_ushort v185, v[248:249], off offset:32
	global_load_ushort v186, v[248:249], off offset:64
	global_load_ushort v187, v[248:249], off offset:96
	v_or_b32_e32 v246, 19, v132
	v_add_u32_e32 v246, s6, v246
	v_mul_u32_u24_e32 v246, 0x1200, v246
	v_lshl_add_u64 v[248:249], s[92:93], 0, v[246:247]
	v_lshl_add_u64 v[248:249], v[248:249], 0, s[26:27]
	v_lshl_add_u64 v[248:249], v[248:249], 0, v[232:233]
	v_lshl_add_u64 v[248:249], v[248:249], 0, s[10:11]
	global_load_ushort v188, v[248:249], off
	global_load_ushort v189, v[248:249], off offset:32
	global_load_ushort v190, v[248:249], off offset:64
	global_load_ushort v191, v[248:249], off offset:96
	ds_read_b128 v[66:69], v114
	ds_read_b128 v[70:73], v114 offset:2048
	ds_read_b128 v[74:77], v113 offset:32768
	ds_read_b128 v[82:85], v113 offset:34816
	ds_read_b128 v[90:93], v113 offset:36864
	ds_read_b128 v[98:101], v113 offset:38912
	s_waitcnt lgkmcnt(3)
	v_mfma_f32_16x16x32_bf16 v[78:81], v[66:69], v[74:77], 0
	v_readlane_b32 s0, v250, 14
	s_add_u32 s4, s0, s26
	v_readlane_b32 s0, v250, 15
	v_mfma_f32_16x16x32_bf16 v[74:77], v[70:73], v[74:77], 0
	s_addc_u32 s5, s0, 0
	s_waitcnt lgkmcnt(2)
	v_mfma_f32_16x16x32_bf16 v[86:89], v[66:69], v[82:85], 0
	v_mfma_f32_16x16x32_bf16 v[82:85], v[70:73], v[82:85], 0
	s_waitcnt lgkmcnt(1)
	v_mfma_f32_16x16x32_bf16 v[94:97], v[66:69], v[90:93], 0
	v_mfma_f32_16x16x32_bf16 v[90:93], v[70:73], v[90:93], 0
	s_waitcnt lgkmcnt(0)
	v_mfma_f32_16x16x32_bf16 v[66:69], v[66:69], v[98:101], 0
	v_mfma_f32_16x16x32_bf16 v[70:73], v[70:73], v[98:101], 0
	ds_read_b128 v[98:101], v125
	ds_read_b128 v[102:105], v125 offset:2048
	ds_read_b128 v[106:109], v124 offset:32768
	s_waitcnt lgkmcnt(0)
	v_mfma_f32_16x16x32_bf16 v[78:81], v[98:101], v[106:109], v[78:81]
	v_mfma_f32_16x16x32_bf16 v[74:77], v[102:105], v[106:109], v[74:77]
	ds_read_b128 v[106:109], v124 offset:34816
	s_waitcnt lgkmcnt(0)
	v_mfma_f32_16x16x32_bf16 v[86:89], v[98:101], v[106:109], v[86:89]
	v_mfma_f32_16x16x32_bf16 v[82:85], v[102:105], v[106:109], v[82:85]
	ds_read_b128 v[106:109], v124 offset:36864
	s_waitcnt lgkmcnt(0)
	v_mfma_f32_16x16x32_bf16 v[94:97], v[98:101], v[106:109], v[94:97]
	v_mfma_f32_16x16x32_bf16 v[90:93], v[102:105], v[106:109], v[90:93]
	ds_read_b128 v[106:109], v124 offset:38912
	s_waitcnt lgkmcnt(0)
	v_mfma_f32_16x16x32_bf16 v[66:69], v[98:101], v[106:109], v[66:69]
	v_mfma_f32_16x16x32_bf16 v[70:73], v[102:105], v[106:109], v[70:73]
	ds_read_b128 v[98:101], v114 offset:16384
	ds_read_b128 v[102:105], v114 offset:18432
	ds_read_b128 v[106:109], v113 offset:40960
	s_waitcnt lgkmcnt(0)
	v_mfma_f32_16x16x32_bf16 v[78:81], v[98:101], v[106:109], v[78:81]
	v_mfma_f32_16x16x32_bf16 v[74:77], v[102:105], v[106:109], v[74:77]
	ds_read_b128 v[106:109], v113 offset:43008
	s_waitcnt lgkmcnt(0)
	v_mfma_f32_16x16x32_bf16 v[86:89], v[98:101], v[106:109], v[86:89]
	v_mfma_f32_16x16x32_bf16 v[106:109], v[102:105], v[106:109], v[82:85]
	s_nop 2
	ds_read_b128 v[82:85], v113 offset:45056
	s_waitcnt lgkmcnt(0)
	v_mfma_f32_16x16x32_bf16 v[116:119], v[98:101], v[82:85], v[94:97]
	v_mfma_f32_16x16x32_bf16 v[120:123], v[102:105], v[82:85], v[90:93]
	ds_read_b128 v[82:85], v113 offset:47104
	s_waitcnt lgkmcnt(0)
	v_mfma_f32_16x16x32_bf16 v[98:101], v[98:101], v[82:85], v[66:69]
	v_mfma_f32_16x16x32_bf16 v[70:73], v[102:105], v[82:85], v[70:73]
	ds_read_b128 v[102:105], v125 offset:16384
	ds_read_b128 v[134:137], v125 offset:18432
	ds_read_b128 v[66:69], v124 offset:40960
	s_waitcnt lgkmcnt(0)
	v_mfma_f32_16x16x32_bf16 v[82:85], v[102:105], v[66:69], v[78:81]
	v_mfma_f32_16x16x32_bf16 v[66:69], v[134:137], v[66:69], v[74:77]
	s_nop 2
	ds_read_b128 v[74:77], v124 offset:43008
	s_waitcnt lgkmcnt(0)
	v_mfma_f32_16x16x32_bf16 v[78:81], v[134:137], v[74:77], v[106:109]
	s_nop 2
	ds_read_b128 v[106:109], v124 offset:47104
	v_mfma_f32_16x16x32_bf16 v[94:97], v[102:105], v[74:77], v[86:89]
	ds_read_b128 v[74:77], v124 offset:45056
	s_waitcnt lgkmcnt(1)
	v_mfma_f32_16x16x32_bf16 v[86:89], v[102:105], v[106:109], v[98:101]
	s_nop 2
	v_and_b32_e32 v99, 64, v207
	v_xor_b32_e32 v98, 1, v207
	v_add_u32_e32 v99, 64, v99
	v_cmp_lt_i32_e32 vcc, v98, v99
	s_waitcnt lgkmcnt(0)
	v_mfma_f32_16x16x32_bf16 v[90:93], v[102:105], v[74:77], v[116:119]
	v_mov_b32_e32 v100, v38
	v_cndmask_b32_e32 v98, v207, v98, vcc
	v_mov_b32_e32 v101, v34
	v_lshlrev_b32_e32 v117, 2, v98
	v_xor_b32_e32 v98, 2, v207
	v_cmp_lt_i32_e32 vcc, v98, v99
	v_mov_b32_e32 v102, v46
	v_mov_b32_e32 v103, v42
	v_cndmask_b32_e32 v98, v207, v98, vcc
	v_lshlrev_b32_e32 v116, 2, v98
	v_xor_b32_e32 v98, 4, v207
	v_cmp_lt_i32_e32 vcc, v98, v99
	v_mfma_f32_16x16x32_bf16 v[70:73], v[134:137], v[106:109], v[70:73]
	v_mov_b32_e32 v107, v62
	v_cndmask_b32_e32 v98, v207, v98, vcc
	v_lshlrev_b32_e32 v114, 2, v98
	v_xor_b32_e32 v98, 8, v207
	v_cmp_lt_i32_e32 vcc, v98, v99
	v_mov_b32_e32 v105, v86
	v_mfma_f32_16x16x32_bf16 v[74:77], v[134:137], v[74:77], v[120:123]
	v_cndmask_b32_e32 v98, v207, v98, vcc
	v_lshlrev_b32_e32 v113, 2, v98
	v_cvt_f32_i32_e32 v98, v133
	v_mul_f32_e32 v98, v98, v131
	v_mul_f32_e32 v98, 0xbfb8aa3b, v98
	v_exp_f32_e32 v99, v98
	v_sub_u32_e32 v98, 0x80, v132
	v_cvt_f32_i32_e32 v98, v98
	v_mul_f32_e32 v98, v98, v130
	v_mul_f32_e32 v98, 0xbfb8aa3b, v98
	v_exp_f32_e32 v98, v98
	s_nop 0
	v_pk_mul_f32 v[100:101], v[98:99], v[100:101]
	s_nop 0
	v_add_f32_e32 v34, v101, v82
	v_pk_mul_f32 v[102:103], v[98:99], v[102:103]
	v_add_f32_e32 v100, v100, v34
	v_add_f32_e32 v34, v103, v94
	v_add_f32_e32 v46, v102, v34
	v_mov_b32_e32 v102, v54
	v_mov_b32_e32 v103, v50
	v_pk_mul_f32 v[102:103], v[98:99], v[102:103]
	v_mul_f32_e32 v104, v46, v46
	v_add_f32_e32 v34, v103, v90
	v_add_f32_e32 v102, v102, v34
	v_mov_b32_e32 v101, v99
	v_mov_b32_e32 v106, v100
	v_pk_fma_f32 v[104:105], v[100:101], v[106:107], v[104:105]
	v_mov_b32_e32 v103, v98
	v_mov_b32_e32 v98, v102
	v_mov_b32_e32 v99, v58
	v_pk_fma_f32 v[104:105], v[102:103], v[98:99], v[104:105]
	v_add_u32_e32 v106, s6, v132
	v_mov_b64_e32 v[98:99], s[92:93]
	v_mad_i64_i32 v[108:109], s[0:1], v106, s3, v[98:99]
	v_lshl_add_u64 v[108:109], v[108:109], 0, s[26:27]
	v_lshl_add_u64 v[118:119], v[108:109], 0, v[0:1]
	v_lshl_add_u64 v[108:109], v[118:119], 0, s[10:11]
	v_add_co_u32_e32 v118, vcc, s7, v118
	v_ashrrev_i32_e32 v107, 31, v106
	s_nop 0
	v_addc_co_u32_e32 v119, vcc, 0, v119, vcc
	v_lshlrev_b64 v[106:107], 11, v[106:107]
	v_lshl_add_u64 v[106:107], s[4:5], 0, v[106:107]
	v_lshl_add_u64 v[106:107], v[106:107], 0, v[0:1]
	s_waitcnt vmcnt(16)
	v_lshlrev_b32_e32 v34, 16, v216
	v_mul_f32_e32 v38, 0xbfb8aa3b, v34
	v_exp_f32_e32 v38, v38
	s_nop 0
	v_add_f32_e32 v38, 1.0, v38
	v_div_scale_f32 v42, s[0:1], v38, v38, v34
	v_rcp_f32_e32 v50, v42
	s_nop 0
	v_fma_f32 v54, -v42, v50, 1.0
	v_fmac_f32_e32 v50, v54, v50
	v_div_scale_f32 v54, vcc, v34, v38, v34
	v_mul_f32_e32 v58, v54, v50
	v_fma_f32 v62, -v42, v58, v54
	v_fmac_f32_e32 v58, v62, v50
	v_fma_f32 v42, -v42, v58, v54
	v_div_fmas_f32 v42, v42, v50, v58
	v_div_fixup_f32 v82, v42, v38, v34
	s_nop 0
	v_lshlrev_b32_e32 v34, 16, v217
	v_mul_f32_e32 v38, 0xbfb8aa3b, v34
	v_exp_f32_e32 v38, v38
	s_nop 0
	v_add_f32_e32 v38, 1.0, v38
	v_div_scale_f32 v42, s[0:1], v38, v38, v34
	v_rcp_f32_e32 v50, v42
	s_nop 0
	v_fma_f32 v54, -v42, v50, 1.0
	v_fmac_f32_e32 v50, v54, v50
	v_div_scale_f32 v54, vcc, v34, v38, v34
	v_mul_f32_e32 v58, v54, v50
	v_fma_f32 v62, -v42, v58, v54
	v_fmac_f32_e32 v58, v62, v50
	v_fma_f32 v42, -v42, v58, v54
	v_div_fmas_f32 v42, v42, v50, v58
	v_div_fixup_f32 v90, v42, v38, v34
	s_nop 0
	v_lshlrev_b32_e32 v34, 16, v218
	v_mul_f32_e32 v38, 0xbfb8aa3b, v34
	v_exp_f32_e32 v38, v38
	s_nop 0
	v_add_f32_e32 v38, 1.0, v38
	v_div_scale_f32 v42, s[0:1], v38, v38, v34
	v_rcp_f32_e32 v50, v42
	s_nop 0
	v_fma_f32 v54, -v42, v50, 1.0
	v_fmac_f32_e32 v50, v54, v50
	v_div_scale_f32 v54, vcc, v34, v38, v34
	v_mul_f32_e32 v58, v54, v50
	v_fma_f32 v62, -v42, v58, v54
	v_fmac_f32_e32 v58, v62, v50
	v_fma_f32 v42, -v42, v58, v54
	v_div_fmas_f32 v42, v42, v50, v58
	v_div_fixup_f32 v94, v42, v38, v34
	s_nop 0
	v_lshlrev_b32_e32 v34, 16, v219
	v_mul_f32_e32 v38, 0xbfb8aa3b, v34
	v_exp_f32_e32 v38, v38
	s_nop 0
	v_add_f32_e32 v38, 1.0, v38
	v_div_scale_f32 v42, s[0:1], v38, v38, v34
	v_rcp_f32_e32 v50, v42
	s_mov_b32 s0, 0x358637bd
	v_fma_f32 v54, -v42, v50, 1.0
	v_fmac_f32_e32 v50, v54, v50
	v_div_scale_f32 v54, vcc, v34, v38, v34
	v_mul_f32_e32 v58, v54, v50
	v_fma_f32 v62, -v42, v58, v54
	v_fmac_f32_e32 v58, v62, v50
	v_fma_f32 v42, -v42, v58, v54
	v_div_fmas_f32 v42, v42, v50, v58
	v_div_fixup_f32 v101, v42, v38, v34
	v_cvt_f32_i32_e32 v34, v127
	v_mov_b32_e32 v42, v47
	v_mov_b32_e32 v50, v55
	v_mul_f32_e32 v34, v34, v131
	v_mul_f32_e32 v34, 0xbfb8aa3b, v34
	v_exp_f32_e32 v109, v34
	v_sub_u32_e32 v34, 0x80, v133
	v_cvt_f32_i32_e32 v34, v34
	v_mov_b32_e32 v55, v109
	v_mul_f32_e32 v34, v34, v130
	v_mul_f32_e32 v34, 0xbfb8aa3b, v34
	v_exp_f32_e32 v108, v34
	v_mov_b32_e32 v34, v39
	v_pk_mul_f32 v[34:35], v[108:109], v[34:35]
	s_nop 0
	v_add_f32_e32 v35, v35, v83
	v_add_f32_e32 v54, v34, v35
	v_pk_mul_f32 v[34:35], v[108:109], v[42:43]
	v_mov_b32_e32 v62, v54
	v_add_f32_e32 v35, v35, v95
	v_add_f32_e32 v83, v34, v35
	v_pk_mul_f32 v[34:35], v[108:109], v[50:51]
	v_mul_f32_e32 v86, v83, v83
	v_add_f32_e32 v35, v35, v91
	v_add_f32_e32 v42, v34, v35
	v_pk_fma_f32 v[34:35], v[54:55], v[62:63], v[86:87]
	v_mov_b32_e32 v43, v108
	v_mov_b32_e32 v58, v42
	v_pk_fma_f32 v[38:39], v[42:43], v[58:59], v[34:35]
	v_mov_b32_e32 v35, v105
	v_mov_b32_e32 v34, v39
	v_mov_b32_e32 v50, v38
	v_mov_b32_e32 v51, v104
	v_pk_fma_f32 v[34:35], v[34:35], v[34:35], v[50:51]
	ds_bpermute_b32 v51, v117, v35
	ds_bpermute_b32 v50, v117, v34
	s_waitcnt lgkmcnt(0)
	v_pk_add_f32 v[34:35], v[34:35], v[50:51]
	ds_bpermute_b32 v51, v116, v35
	ds_bpermute_b32 v50, v116, v34
	s_waitcnt lgkmcnt(0)
	v_pk_add_f32 v[34:35], v[34:35], v[50:51]
	ds_bpermute_b32 v51, v114, v35
	ds_bpermute_b32 v50, v114, v34
	s_waitcnt lgkmcnt(0)
	v_pk_add_f32 v[34:35], v[34:35], v[50:51]
	ds_bpermute_b32 v51, v113, v35
	ds_bpermute_b32 v50, v113, v34
	s_waitcnt lgkmcnt(0)
	v_pk_add_f32 v[50:51], v[34:35], v[50:51]
	v_mov_b64_e32 v[34:35], s[0:1]
	v_pk_fma_f32 v[50:51], v[50:51], s[12:13], v[34:35] op_sel_hi:[1,0,0]
	s_nop 0
	v_mul_f32_e32 v38, 0x4b800000, v51
	v_cmp_gt_f32_e64 s[0:1], s8, v51
	v_cmp_gt_f32_e32 vcc, s8, v50
	s_nop 0
	v_cndmask_b32_e64 v38, v51, v38, s[0:1]
	v_rsq_f32_e32 v38, v38
	s_nop 0
	v_mul_f32_e32 v43, 0x45800000, v38
	v_cndmask_b32_e64 v38, v38, v43, s[0:1]
	v_mul_f32_e32 v43, v100, v38
	v_mul_f32_e32 v43, v82, v43
	v_cvt_pk_bf16_f32 v43, v43, s0
	global_store_short v[106:107], v43, off
	v_mul_f32_e32 v43, v46, v38
	v_mul_f32_e32 v43, v43, v90
	v_cvt_pk_bf16_f32 v43, v43, s0
	global_store_short v[106:107], v43, off offset:32
	v_mul_f32_e32 v43, v102, v38
	v_mul_f32_e32 v38, v105, v38
	v_mul_f32_e32 v38, v38, v101
	v_cvt_pk_bf16_f32 v38, v38, s0
	global_store_short v[106:107], v38, off offset:96
	v_mul_f32_e32 v38, 0x4b800000, v50
	v_cndmask_b32_e32 v38, v50, v38, vcc
	v_rsq_f32_e32 v38, v38
	v_mul_f32_e32 v43, v43, v94
	v_add_u32_e32 v46, s6, v133
	v_cvt_pk_bf16_f32 v43, v43, s0
	v_mad_i64_i32 v[50:51], s[0:1], v46, s3, v[98:99]
	v_ashrrev_i32_e32 v47, 31, v46
	v_lshl_add_u64 v[50:51], v[50:51], 0, s[26:27]
	global_store_short v[106:107], v43, off offset:64
	v_mul_f32_e32 v43, 0x45800000, v38
	v_lshlrev_b64 v[46:47], 11, v[46:47]
	v_lshl_add_u64 v[50:51], v[50:51], 0, v[0:1]
	v_cndmask_b32_e32 v38, v38, v43, vcc
	v_lshl_add_u64 v[58:59], s[4:5], 0, v[46:47]
	v_lshl_add_u64 v[46:47], v[50:51], 0, s[10:11]
	v_add_co_u32_e32 v50, vcc, s7, v50
	v_mul_f32_e32 v42, v42, v38
	s_nop 0
	v_addc_co_u32_e32 v51, vcc, 0, v51, vcc
	v_mul_f32_e32 v50, v54, v38
	s_nop 0
	v_lshlrev_b32_e32 v43, 16, v220
	v_mul_f32_e32 v51, 0xbfb8aa3b, v43
	v_exp_f32_e32 v51, v51
	s_nop 0
	v_add_f32_e32 v51, 1.0, v51
	v_div_scale_f32 v54, s[0:1], v51, v51, v43
	v_rcp_f32_e32 v55, v54
	s_nop 0
	v_fma_f32 v62, -v54, v55, 1.0
	v_fmac_f32_e32 v55, v62, v55
	v_div_scale_f32 v62, vcc, v43, v51, v43
	v_mul_f32_e32 v63, v62, v55
	v_fma_f32 v82, -v54, v63, v62
	v_fmac_f32_e32 v63, v82, v55
	v_fma_f32 v54, -v54, v63, v62
	v_div_fmas_f32 v54, v54, v55, v63
	v_div_fixup_f32 v43, v54, v51, v43
	v_mul_f32_e32 v43, v43, v50
	v_cvt_pk_bf16_f32 v43, v43, s0
	v_lshl_add_u64 v[50:51], v[58:59], 0, v[0:1]
	global_store_short v[50:51], v43, off
	v_mul_f32_e32 v54, v83, v38
	v_mul_f32_e32 v38, v39, v38
	s_nop 0
	v_lshlrev_b32_e32 v43, 16, v221
	v_mul_f32_e32 v55, 0xbfb8aa3b, v43
	v_exp_f32_e32 v55, v55
	s_nop 0
	v_add_f32_e32 v55, 1.0, v55
	v_div_scale_f32 v58, s[0:1], v55, v55, v43
	v_rcp_f32_e32 v59, v58
	s_nop 0
	v_fma_f32 v62, -v58, v59, 1.0
	v_fmac_f32_e32 v59, v62, v59
	v_div_scale_f32 v62, vcc, v43, v55, v43
	v_mul_f32_e32 v63, v62, v59
	v_fma_f32 v82, -v58, v63, v62
	v_fmac_f32_e32 v63, v82, v59
	v_fma_f32 v58, -v58, v63, v62
	v_div_fmas_f32 v58, v58, v59, v63
	v_div_fixup_f32 v43, v58, v55, v43
	v_mul_f32_e32 v43, v54, v43
	v_cvt_pk_bf16_f32 v43, v43, s0
	global_store_short v[50:51], v43, off offset:32
	s_nop 0
	v_lshlrev_b32_e32 v43, 16, v222
	v_mul_f32_e32 v54, 0xbfb8aa3b, v43
	v_exp_f32_e32 v54, v54
	s_nop 0
	v_add_f32_e32 v54, 1.0, v54
	v_div_scale_f32 v55, s[0:1], v54, v54, v43
	v_rcp_f32_e32 v58, v55
	s_nop 0
	v_fma_f32 v59, -v55, v58, 1.0
	v_fmac_f32_e32 v58, v59, v58
	v_div_scale_f32 v59, vcc, v43, v54, v43
	v_mul_f32_e32 v62, v59, v58
	v_fma_f32 v63, -v55, v62, v59
	v_fmac_f32_e32 v62, v63, v58
	v_fma_f32 v55, -v55, v62, v59
	v_div_fmas_f32 v55, v55, v58, v62
	v_div_fixup_f32 v43, v55, v54, v43
	v_mul_f32_e32 v42, v42, v43
	v_cvt_pk_bf16_f32 v42, v42, s0
	global_store_short v[50:51], v42, off offset:64
	s_nop 0
	v_lshlrev_b32_e32 v42, 16, v223
	v_mul_f32_e32 v39, 0xbfb8aa3b, v42
	v_exp_f32_e32 v39, v39
	s_nop 0
	v_add_f32_e32 v39, 1.0, v39
	v_div_scale_f32 v43, s[0:1], v39, v39, v42
	v_rcp_f32_e32 v46, v43
	s_nop 0
	v_fma_f32 v47, -v43, v46, 1.0
	v_fmac_f32_e32 v46, v47, v46
	v_div_scale_f32 v47, vcc, v42, v39, v42
	v_mul_f32_e32 v54, v47, v46
	v_fma_f32 v55, -v43, v54, v47
	v_fmac_f32_e32 v54, v55, v46
	v_fma_f32 v43, -v43, v54, v47
	v_div_fmas_f32 v43, v43, v46, v54
	v_div_fixup_f32 v39, v43, v39, v42
	v_mul_f32_e32 v38, v38, v39
	v_cvt_pk_bf16_f32 v38, v38, s0
	global_store_short v[50:51], v38, off offset:96
	v_cvt_f32_i32_e32 v38, v126
	v_mov_b32_e32 v39, v36
	v_mov_b32_e32 v42, v48
	v_mov_b32_e32 v43, v44
	v_mul_f32_e32 v38, v38, v131
	v_mul_f32_e32 v38, 0xbfb8aa3b, v38
	v_exp_f32_e32 v47, v38
	v_sub_u32_e32 v38, 0x80, v127
	v_cvt_f32_i32_e32 v38, v38
	v_mov_b32_e32 v55, v64
	v_mov_b32_e32 v51, v88
	v_mul_f32_e32 v38, v38, v130
	v_mul_f32_e32 v38, 0xbfb8aa3b, v38
	v_exp_f32_e32 v46, v38
	v_mov_b32_e32 v38, v40
	v_pk_mul_f32 v[38:39], v[46:47], v[38:39]
	s_nop 0
	v_add_f32_e32 v36, v39, v84
	v_pk_mul_f32 v[42:43], v[46:47], v[42:43]
	v_add_f32_e32 v38, v38, v36
	v_add_f32_e32 v36, v43, v96
	v_add_f32_e32 v58, v42, v36
	v_mov_b32_e32 v42, v56
	v_mov_b32_e32 v43, v52
	v_pk_mul_f32 v[42:43], v[46:47], v[42:43]
	v_mul_f32_e32 v50, v58, v58
	v_add_f32_e32 v36, v43, v92
	v_add_f32_e32 v42, v42, v36
	v_mov_b32_e32 v39, v47
	v_mov_b32_e32 v54, v38
	v_pk_fma_f32 v[50:51], v[38:39], v[54:55], v[50:51]
	v_mov_b32_e32 v43, v46
	v_mov_b32_e32 v46, v42
	v_mov_b32_e32 v47, v60
	v_pk_fma_f32 v[46:47], v[42:43], v[46:47], v[50:51]
	v_add_u32_e32 v50, s6, v127
	v_mad_i64_i32 v[54:55], s[0:1], v50, s3, v[98:99]
	v_lshl_add_u64 v[54:55], v[54:55], 0, s[26:27]
	v_lshl_add_u64 v[62:63], v[54:55], 0, v[0:1]
	v_lshl_add_u64 v[54:55], v[62:63], 0, s[10:11]
	v_add_co_u32_e32 v62, vcc, s7, v62
	v_ashrrev_i32_e32 v51, 31, v50
	s_nop 0
	v_addc_co_u32_e32 v63, vcc, 0, v63, vcc
	v_lshlrev_b64 v[50:51], 11, v[50:51]
	v_lshl_add_u64 v[50:51], s[4:5], 0, v[50:51]
	v_lshl_add_u64 v[50:51], v[50:51], 0, v[0:1]
	s_nop 0
	v_lshlrev_b32_e32 v36, 16, v224
	v_mul_f32_e32 v39, 0xbfb8aa3b, v36
	v_exp_f32_e32 v39, v39
	s_nop 0
	v_add_f32_e32 v39, 1.0, v39
	v_div_scale_f32 v40, s[0:1], v39, v39, v36
	v_rcp_f32_e32 v43, v40
	s_nop 0
	v_fma_f32 v44, -v40, v43, 1.0
	v_fmac_f32_e32 v43, v44, v43
	v_div_scale_f32 v44, vcc, v36, v39, v36
	v_mul_f32_e32 v48, v44, v43
	v_fma_f32 v52, -v40, v48, v44
	v_fmac_f32_e32 v48, v52, v43
	v_fma_f32 v40, -v40, v48, v44
	v_div_fmas_f32 v40, v40, v43, v48
	v_div_fixup_f32 v39, v40, v39, v36
	s_nop 0
	v_lshlrev_b32_e32 v36, 16, v225
	v_mul_f32_e32 v40, 0xbfb8aa3b, v36
	v_exp_f32_e32 v40, v40
	s_nop 0
	v_add_f32_e32 v40, 1.0, v40
	v_div_scale_f32 v43, s[0:1], v40, v40, v36
	v_rcp_f32_e32 v44, v43
	s_nop 0
	v_fma_f32 v48, -v43, v44, 1.0
	v_fmac_f32_e32 v44, v48, v44
	v_div_scale_f32 v48, vcc, v36, v40, v36
	v_mul_f32_e32 v52, v48, v44
	v_fma_f32 v56, -v43, v52, v48
	v_fmac_f32_e32 v52, v56, v44
	v_fma_f32 v43, -v43, v52, v48
	v_div_fmas_f32 v43, v43, v44, v52
	v_div_fixup_f32 v43, v43, v40, v36
	s_nop 0
	v_lshlrev_b32_e32 v36, 16, v226
	v_mul_f32_e32 v40, 0xbfb8aa3b, v36
	v_exp_f32_e32 v40, v40
	s_nop 0
	v_add_f32_e32 v40, 1.0, v40
	v_div_scale_f32 v44, s[0:1], v40, v40, v36
	v_rcp_f32_e32 v48, v44
	s_nop 0
	v_fma_f32 v52, -v44, v48, 1.0
	v_fmac_f32_e32 v48, v52, v48
	v_div_scale_f32 v52, vcc, v36, v40, v36
	v_mul_f32_e32 v56, v52, v48
	v_fma_f32 v59, -v44, v56, v52
	v_fmac_f32_e32 v56, v59, v48
	v_fma_f32 v44, -v44, v56, v52
	v_div_fmas_f32 v44, v44, v48, v56
	v_div_fixup_f32 v56, v44, v40, v36
	s_nop 0
	v_lshlrev_b32_e32 v36, 16, v227
	v_mul_f32_e32 v40, 0xbfb8aa3b, v36
	v_exp_f32_e32 v40, v40
	s_nop 0
	v_add_f32_e32 v40, 1.0, v40
	v_div_scale_f32 v44, s[0:1], v40, v40, v36
	v_rcp_f32_e32 v48, v44
	s_nop 0
	v_fma_f32 v52, -v44, v48, 1.0
	v_fmac_f32_e32 v48, v52, v48
	v_div_scale_f32 v52, vcc, v36, v40, v36
	v_mul_f32_e32 v54, v52, v48
	v_fma_f32 v55, -v44, v54, v52
	v_fmac_f32_e32 v54, v55, v48
	v_fma_f32 v44, -v44, v54, v52
	v_div_fmas_f32 v44, v44, v48, v54
	v_div_fixup_f32 v59, v44, v40, v36
	v_add_u32_e32 v36, 4, v132
	v_cvt_f32_i32_e32 v36, v36
	v_mov_b32_e32 v44, v49
	v_mov_b32_e32 v52, v57
	v_mul_f32_e32 v36, v36, v131
	v_mul_f32_e32 v36, 0xbfb8aa3b, v36
	v_exp_f32_e32 v55, v36
	v_sub_u32_e32 v36, 0x80, v126
	v_cvt_f32_i32_e32 v36, v36
	v_mov_b32_e32 v49, v55
	v_mul_f32_e32 v36, v36, v130
	v_mul_f32_e32 v36, 0xbfb8aa3b, v36
	v_exp_f32_e32 v54, v36
	v_mov_b32_e32 v36, v41
	v_pk_mul_f32 v[36:37], v[54:55], v[36:37]
	s_nop 0
	v_add_f32_e32 v37, v37, v85
	v_add_f32_e32 v48, v36, v37
	v_pk_mul_f32 v[36:37], v[54:55], v[44:45]
	v_mov_b32_e32 v64, v48
	v_add_f32_e32 v37, v37, v97
	v_add_f32_e32 v62, v36, v37
	v_pk_mul_f32 v[36:37], v[54:55], v[52:53]
	v_mul_f32_e32 v88, v62, v62
	v_add_f32_e32 v37, v37, v93
	v_add_f32_e32 v40, v36, v37
	v_pk_fma_f32 v[36:37], v[48:49], v[64:65], v[88:89]
	v_mov_b32_e32 v41, v54
	v_mov_b32_e32 v60, v40
	v_pk_fma_f32 v[36:37], v[40:41], v[60:61], v[36:37]
	v_mov_b32_e32 v45, v47
	v_mov_b32_e32 v44, v37
	v_mov_b32_e32 v52, v36
	v_mov_b32_e32 v53, v46
	v_pk_fma_f32 v[44:45], v[44:45], v[44:45], v[52:53]
	ds_bpermute_b32 v53, v117, v45
	ds_bpermute_b32 v52, v117, v44
	s_waitcnt lgkmcnt(0)
	v_pk_add_f32 v[44:45], v[44:45], v[52:53]
	ds_bpermute_b32 v53, v116, v45
	ds_bpermute_b32 v52, v116, v44
	s_waitcnt lgkmcnt(0)
	v_pk_add_f32 v[44:45], v[44:45], v[52:53]
	ds_bpermute_b32 v53, v114, v45
	ds_bpermute_b32 v52, v114, v44
	s_waitcnt lgkmcnt(0)
	v_pk_add_f32 v[44:45], v[44:45], v[52:53]
	ds_bpermute_b32 v53, v113, v45
	ds_bpermute_b32 v52, v113, v44
	s_waitcnt lgkmcnt(0)
	v_pk_add_f32 v[44:45], v[44:45], v[52:53]
	s_nop 0
	v_pk_fma_f32 v[44:45], v[44:45], s[12:13], v[34:35] op_sel_hi:[1,0,0]
	s_nop 0
	v_mul_f32_e32 v36, 0x4b800000, v45
	v_cmp_gt_f32_e64 s[0:1], s8, v45
	v_cmp_gt_f32_e32 vcc, s8, v44
	s_nop 0
	v_cndmask_b32_e64 v36, v45, v36, s[0:1]
	v_rsq_f32_e32 v36, v36
	s_nop 0
	v_mul_f32_e32 v41, 0x45800000, v36
	v_cndmask_b32_e64 v36, v36, v41, s[0:1]
	v_mul_f32_e32 v38, v38, v36
	v_mul_f32_e32 v38, v39, v38
	v_cvt_pk_bf16_f32 v38, v38, s0
	global_store_short v[50:51], v38, off
	v_mul_f32_e32 v38, v58, v36
	v_mul_f32_e32 v38, v38, v43
	v_cvt_pk_bf16_f32 v38, v38, s0
	global_store_short v[50:51], v38, off offset:32
	v_mul_f32_e32 v38, v42, v36
	v_mul_f32_e32 v36, v47, v36
	v_mul_f32_e32 v36, v36, v59
	v_cvt_pk_bf16_f32 v36, v36, s0
	global_store_short v[50:51], v36, off offset:96
	v_mul_f32_e32 v36, 0x4b800000, v44
	v_cndmask_b32_e32 v36, v44, v36, vcc
	v_rsq_f32_e32 v36, v36
	v_mul_f32_e32 v38, v38, v56
	v_cvt_pk_bf16_f32 v38, v38, s0
	global_store_short v[50:51], v38, off offset:64
	v_mul_f32_e32 v38, 0x45800000, v36
	v_cndmask_b32_e32 v36, v36, v38, vcc
	v_add_u32_e32 v38, s6, v126
	v_mad_i64_i32 v[42:43], s[0:1], v38, s3, v[98:99]
	v_ashrrev_i32_e32 v39, 31, v38
	v_lshl_add_u64 v[42:43], v[42:43], 0, s[26:27]
	v_lshlrev_b64 v[38:39], 11, v[38:39]
	v_lshl_add_u64 v[42:43], v[42:43], 0, v[0:1]
	v_lshl_add_u64 v[44:45], s[4:5], 0, v[38:39]
	v_lshl_add_u64 v[38:39], v[42:43], 0, s[10:11]
	v_add_co_u32_e32 v42, vcc, s7, v42
	v_mul_f32_e32 v40, v40, v36
	s_nop 0
	v_addc_co_u32_e32 v43, vcc, 0, v43, vcc
	v_mul_f32_e32 v42, v48, v36
	s_nop 0
	v_lshlrev_b32_e32 v41, 16, v228
	v_mul_f32_e32 v43, 0xbfb8aa3b, v41
	v_exp_f32_e32 v43, v43
	s_nop 0
	v_add_f32_e32 v43, 1.0, v43
	v_div_scale_f32 v46, s[0:1], v43, v43, v41
	v_rcp_f32_e32 v47, v46
	s_nop 0
	v_fma_f32 v48, -v46, v47, 1.0
	v_fmac_f32_e32 v47, v48, v47
	v_div_scale_f32 v48, vcc, v41, v43, v41
	v_mul_f32_e32 v49, v48, v47
	v_fma_f32 v50, -v46, v49, v48
	v_fmac_f32_e32 v49, v50, v47
	v_fma_f32 v46, -v46, v49, v48
	v_div_fmas_f32 v46, v46, v47, v49
	v_div_fixup_f32 v41, v46, v43, v41
	v_mul_f32_e32 v41, v41, v42
	v_cvt_pk_bf16_f32 v41, v41, s0
	v_lshl_add_u64 v[42:43], v[44:45], 0, v[0:1]
	global_store_short v[42:43], v41, off
	v_mul_f32_e32 v44, v62, v36
	v_mul_f32_e32 v36, v37, v36
	s_nop 0
	v_lshlrev_b32_e32 v41, 16, v229
	v_mul_f32_e32 v45, 0xbfb8aa3b, v41
	v_exp_f32_e32 v45, v45
	s_nop 0
	v_add_f32_e32 v45, 1.0, v45
	v_div_scale_f32 v46, s[0:1], v45, v45, v41
	v_rcp_f32_e32 v47, v46
	s_nop 0
	v_fma_f32 v48, -v46, v47, 1.0
	v_fmac_f32_e32 v47, v48, v47
	v_div_scale_f32 v48, vcc, v41, v45, v41
	v_mul_f32_e32 v49, v48, v47
	v_fma_f32 v50, -v46, v49, v48
	v_fmac_f32_e32 v49, v50, v47
	v_fma_f32 v46, -v46, v49, v48
	v_div_fmas_f32 v46, v46, v47, v49
	v_div_fixup_f32 v41, v46, v45, v41
	v_mul_f32_e32 v41, v44, v41
	v_cvt_pk_bf16_f32 v41, v41, s0
	global_store_short v[42:43], v41, off offset:32
	s_nop 0
	v_lshlrev_b32_e32 v41, 16, v230
	v_mul_f32_e32 v44, 0xbfb8aa3b, v41
	v_exp_f32_e32 v44, v44
	s_nop 0
	v_lshlrev_b32_e32 v38, 16, v231
	v_add_f32_e32 v44, 1.0, v44
	v_div_scale_f32 v45, s[0:1], v44, v44, v41
	v_rcp_f32_e32 v46, v45
	v_mul_f32_e32 v37, 0xbfb8aa3b, v38
	v_exp_f32_e32 v37, v37
	v_fma_f32 v47, -v45, v46, 1.0
	v_fmac_f32_e32 v46, v47, v46
	v_div_scale_f32 v47, vcc, v41, v44, v41
	v_mul_f32_e32 v48, v47, v46
	v_fma_f32 v49, -v45, v48, v47
	v_fmac_f32_e32 v48, v49, v46
	v_fma_f32 v45, -v45, v48, v47
	v_div_fmas_f32 v45, v45, v46, v48
	v_div_fixup_f32 v41, v45, v44, v41
	v_mul_f32_e32 v40, v40, v41
	v_add_f32_e32 v37, 1.0, v37
	v_cvt_pk_bf16_f32 v40, v40, s0
	v_div_scale_f32 v39, s[0:1], v37, v37, v38
	global_store_short v[42:43], v40, off offset:64
	v_rcp_f32_e32 v40, v39
	s_nop 0
	v_fma_f32 v41, -v39, v40, 1.0
	v_fmac_f32_e32 v40, v41, v40
	v_div_scale_f32 v41, vcc, v38, v37, v38
	v_mul_f32_e32 v44, v41, v40
	v_fma_f32 v45, -v39, v44, v41
	v_fmac_f32_e32 v44, v45, v40
	v_fma_f32 v39, -v39, v44, v41
	v_div_fmas_f32 v39, v39, v40, v44
	v_div_fixup_f32 v37, v39, v37, v38
	v_mul_f32_e32 v36, v36, v37
	v_cvt_pk_bf16_f32 v36, v36, s0
	global_store_short v[42:43], v36, off offset:96
	v_cvt_f32_i32_e32 v36, v112
	v_mov_b32_e32 v37, v2
	v_mov_b32_e32 v38, v14
	v_mov_b32_e32 v39, v10
	v_mul_f32_e32 v36, v36, v131
	v_mul_f32_e32 v36, 0xbfb8aa3b, v36
	v_exp_f32_e32 v41, v36
	v_sub_u32_e32 v36, 0x80, v115
	v_cvt_f32_i32_e32 v36, v36
	v_mov_b32_e32 v45, v30
	v_mov_b32_e32 v43, v70
	v_mul_f32_e32 v36, v36, v130
	v_mul_f32_e32 v36, 0xbfb8aa3b, v36
	v_exp_f32_e32 v40, v36
	v_mov_b32_e32 v36, v6
	v_pk_mul_f32 v[36:37], v[40:41], v[36:37]
	s_nop 0
	v_add_f32_e32 v2, v37, v66
	v_pk_mul_f32 v[38:39], v[40:41], v[38:39]
	v_add_f32_e32 v36, v36, v2
	v_add_f32_e32 v2, v39, v78
	v_add_f32_e32 v46, v38, v2
	v_mov_b32_e32 v38, v22
	v_mov_b32_e32 v39, v18
	v_pk_mul_f32 v[38:39], v[40:41], v[38:39]
	v_mul_f32_e32 v42, v46, v46
	v_add_f32_e32 v2, v39, v74
	v_add_f32_e32 v38, v38, v2
	v_mov_b32_e32 v37, v41
	v_mov_b32_e32 v44, v36
	v_pk_fma_f32 v[42:43], v[36:37], v[44:45], v[42:43]
	v_mov_b32_e32 v39, v40
	v_mov_b32_e32 v40, v38
	v_mov_b32_e32 v41, v26
	v_pk_fma_f32 v[40:41], v[38:39], v[40:41], v[42:43]
	v_add_u32_e32 v42, s6, v115
	v_mad_i64_i32 v[44:45], s[0:1], v42, s3, v[98:99]
	v_lshl_add_u64 v[44:45], v[44:45], 0, s[26:27]
	v_lshl_add_u64 v[48:49], v[44:45], 0, v[0:1]
	v_lshl_add_u64 v[44:45], v[48:49], 0, s[10:11]
	v_add_co_u32_e32 v48, vcc, s7, v48
	v_ashrrev_i32_e32 v43, 31, v42
	s_nop 0
	v_addc_co_u32_e32 v49, vcc, 0, v49, vcc
	v_lshlrev_b64 v[42:43], 11, v[42:43]
	v_lshl_add_u64 v[42:43], s[4:5], 0, v[42:43]
	v_lshl_add_u64 v[42:43], v[42:43], 0, v[0:1]
	s_waitcnt vmcnt(16)
	v_lshlrev_b32_e32 v2, 16, v176
	v_mul_f32_e32 v6, 0xbfb8aa3b, v2
	v_exp_f32_e32 v6, v6
	s_nop 0
	v_add_f32_e32 v6, 1.0, v6
	v_div_scale_f32 v10, s[0:1], v6, v6, v2
	v_rcp_f32_e32 v14, v10
	s_nop 0
	v_fma_f32 v18, -v10, v14, 1.0
	v_fmac_f32_e32 v14, v18, v14
	v_div_scale_f32 v18, vcc, v2, v6, v2
	v_mul_f32_e32 v22, v18, v14
	v_fma_f32 v26, -v10, v22, v18
	v_fmac_f32_e32 v22, v26, v14
	v_fma_f32 v10, -v10, v22, v18
	v_div_fmas_f32 v10, v10, v14, v22
	v_div_fixup_f32 v22, v10, v6, v2
	s_nop 0
	v_lshlrev_b32_e32 v2, 16, v177
	v_mul_f32_e32 v6, 0xbfb8aa3b, v2
	v_exp_f32_e32 v6, v6
	s_nop 0
	v_add_f32_e32 v6, 1.0, v6
	v_div_scale_f32 v10, s[0:1], v6, v6, v2
	v_rcp_f32_e32 v14, v10
	s_nop 0
	v_fma_f32 v18, -v10, v14, 1.0
	v_fmac_f32_e32 v14, v18, v14
	v_div_scale_f32 v18, vcc, v2, v6, v2
	v_mul_f32_e32 v26, v18, v14
	v_fma_f32 v30, -v10, v26, v18
	v_fmac_f32_e32 v26, v30, v14
	v_fma_f32 v10, -v10, v26, v18
	v_div_fmas_f32 v10, v10, v14, v26
	v_div_fixup_f32 v37, v10, v6, v2
	s_nop 0
	v_lshlrev_b32_e32 v2, 16, v178
	v_mul_f32_e32 v6, 0xbfb8aa3b, v2
	v_exp_f32_e32 v6, v6
	s_nop 0
	v_add_f32_e32 v6, 1.0, v6
	v_div_scale_f32 v10, s[0:1], v6, v6, v2
	v_rcp_f32_e32 v14, v10
	s_nop 0
	v_fma_f32 v18, -v10, v14, 1.0
	v_fmac_f32_e32 v14, v18, v14
	v_div_scale_f32 v18, vcc, v2, v6, v2
	v_mul_f32_e32 v26, v18, v14
	v_fma_f32 v30, -v10, v26, v18
	v_fmac_f32_e32 v26, v30, v14
	v_fma_f32 v10, -v10, v26, v18
	v_div_fmas_f32 v10, v10, v14, v26
	v_div_fixup_f32 v39, v10, v6, v2
	s_nop 0
	v_lshlrev_b32_e32 v2, 16, v179
	v_mul_f32_e32 v6, 0xbfb8aa3b, v2
	v_exp_f32_e32 v6, v6
	s_nop 0
	v_add_f32_e32 v6, 1.0, v6
	v_div_scale_f32 v10, s[0:1], v6, v6, v2
	v_rcp_f32_e32 v14, v10
	s_nop 0
	v_fma_f32 v18, -v10, v14, 1.0
	v_fmac_f32_e32 v14, v18, v14
	v_div_scale_f32 v18, vcc, v2, v6, v2
	v_mul_f32_e32 v26, v18, v14
	v_fma_f32 v30, -v10, v26, v18
	v_fmac_f32_e32 v26, v30, v14
	v_fma_f32 v10, -v10, v26, v18
	v_div_fmas_f32 v10, v10, v14, v26
	v_div_fixup_f32 v47, v10, v6, v2
	v_cvt_f32_i32_e32 v2, v111
	v_mov_b32_e32 v10, v15
	v_mov_b32_e32 v18, v23
	v_mul_f32_e32 v2, v2, v131
	v_mul_f32_e32 v2, 0xbfb8aa3b, v2
	v_exp_f32_e32 v45, v2
	v_sub_u32_e32 v2, 0x80, v112
	v_cvt_f32_i32_e32 v2, v2
	v_mov_b32_e32 v15, v45
	v_mul_f32_e32 v2, v2, v130
	v_mul_f32_e32 v2, 0xbfb8aa3b, v2
	v_exp_f32_e32 v44, v2
	v_mov_b32_e32 v2, v7
	v_pk_mul_f32 v[2:3], v[44:45], v[2:3]
	s_nop 0
	v_add_f32_e32 v3, v3, v67
	v_add_f32_e32 v14, v2, v3
	v_pk_mul_f32 v[2:3], v[44:45], v[10:11]
	v_mov_b32_e32 v30, v14
	v_add_f32_e32 v3, v3, v79
	v_add_f32_e32 v48, v2, v3
	v_pk_mul_f32 v[2:3], v[44:45], v[18:19]
	v_mul_f32_e32 v70, v48, v48
	v_add_f32_e32 v3, v3, v75
	v_add_f32_e32 v6, v2, v3
	v_pk_fma_f32 v[2:3], v[14:15], v[30:31], v[70:71]
	v_mov_b32_e32 v7, v44
	v_mov_b32_e32 v26, v6
	v_pk_fma_f32 v[2:3], v[6:7], v[26:27], v[2:3]
	v_mov_b32_e32 v11, v41
	v_mov_b32_e32 v10, v3
	v_mov_b32_e32 v18, v2
	v_mov_b32_e32 v19, v40
	v_pk_fma_f32 v[10:11], v[10:11], v[10:11], v[18:19]
	ds_bpermute_b32 v19, v117, v11
	ds_bpermute_b32 v18, v117, v10
	s_waitcnt lgkmcnt(0)
	v_pk_add_f32 v[10:11], v[10:11], v[18:19]
	ds_bpermute_b32 v19, v116, v11
	ds_bpermute_b32 v18, v116, v10
	s_waitcnt lgkmcnt(0)
	v_pk_add_f32 v[10:11], v[10:11], v[18:19]
	ds_bpermute_b32 v19, v114, v11
	ds_bpermute_b32 v18, v114, v10
	s_waitcnt lgkmcnt(0)
	v_pk_add_f32 v[10:11], v[10:11], v[18:19]
	ds_bpermute_b32 v19, v113, v11
	ds_bpermute_b32 v18, v113, v10
	s_waitcnt lgkmcnt(0)
	v_pk_add_f32 v[10:11], v[10:11], v[18:19]
	s_nop 0
	v_pk_fma_f32 v[10:11], v[10:11], s[12:13], v[34:35] op_sel_hi:[1,0,0]
	s_nop 0
	v_mul_f32_e32 v2, 0x4b800000, v11
	v_cmp_gt_f32_e64 s[0:1], s8, v11
	v_cmp_gt_f32_e32 vcc, s8, v10
	s_nop 0
	v_cndmask_b32_e64 v2, v11, v2, s[0:1]
	v_rsq_f32_e32 v2, v2
	s_nop 0
	v_mul_f32_e32 v7, 0x45800000, v2
	v_cndmask_b32_e64 v2, v2, v7, s[0:1]
	v_mul_f32_e32 v7, v36, v2
	v_mul_f32_e32 v7, v22, v7
	v_cvt_pk_bf16_f32 v7, v7, s0
	global_store_short v[42:43], v7, off
	v_mul_f32_e32 v7, v46, v2
	v_mul_f32_e32 v7, v7, v37
	v_cvt_pk_bf16_f32 v7, v7, s0
	global_store_short v[42:43], v7, off offset:32
	v_mul_f32_e32 v7, v38, v2
	v_mul_f32_e32 v2, v41, v2
	v_mul_f32_e32 v2, v2, v47
	v_cvt_pk_bf16_f32 v2, v2, s0
	global_store_short v[42:43], v2, off offset:96
	v_mul_f32_e32 v2, 0x4b800000, v10
	v_cndmask_b32_e32 v2, v10, v2, vcc
	v_rsq_f32_e32 v2, v2
	v_mul_f32_e32 v7, v7, v39
	v_add_u32_e32 v10, s6, v112
	v_cvt_pk_bf16_f32 v7, v7, s0
	v_mad_i64_i32 v[18:19], s[0:1], v10, s3, v[98:99]
	v_ashrrev_i32_e32 v11, 31, v10
	v_lshl_add_u64 v[18:19], v[18:19], 0, s[26:27]
	global_store_short v[42:43], v7, off offset:64
	v_mul_f32_e32 v7, 0x45800000, v2
	v_lshlrev_b64 v[10:11], 11, v[10:11]
	v_lshl_add_u64 v[18:19], v[18:19], 0, v[0:1]
	v_cndmask_b32_e32 v2, v2, v7, vcc
	v_lshl_add_u64 v[22:23], s[4:5], 0, v[10:11]
	v_lshl_add_u64 v[10:11], v[18:19], 0, s[10:11]
	v_add_co_u32_e32 v18, vcc, s7, v18
	v_mul_f32_e32 v14, v14, v2
	s_nop 0
	v_addc_co_u32_e32 v19, vcc, 0, v19, vcc
	v_mul_f32_e32 v6, v6, v2
	s_nop 0
	v_lshlrev_b32_e32 v7, 16, v180
	v_mul_f32_e32 v15, 0xbfb8aa3b, v7
	v_exp_f32_e32 v15, v15
	s_nop 0
	v_add_f32_e32 v15, 1.0, v15
	v_div_scale_f32 v18, s[0:1], v15, v15, v7
	v_rcp_f32_e32 v19, v18
	s_nop 0
	v_fma_f32 v26, -v18, v19, 1.0
	v_fmac_f32_e32 v19, v26, v19
	v_div_scale_f32 v26, vcc, v7, v15, v7
	v_mul_f32_e32 v27, v26, v19
	v_fma_f32 v30, -v18, v27, v26
	v_fmac_f32_e32 v27, v30, v19
	v_fma_f32 v18, -v18, v27, v26
	v_div_fmas_f32 v18, v18, v19, v27
	v_div_fixup_f32 v7, v18, v15, v7
	v_mul_f32_e32 v7, v7, v14
	v_cvt_pk_bf16_f32 v7, v7, s0
	v_lshl_add_u64 v[14:15], v[22:23], 0, v[0:1]
	global_store_short v[14:15], v7, off
	v_mul_f32_e32 v18, v48, v2
	v_mul_f32_e32 v2, v3, v2
	s_nop 0
	v_lshlrev_b32_e32 v7, 16, v181
	v_mul_f32_e32 v19, 0xbfb8aa3b, v7
	v_exp_f32_e32 v19, v19
	s_nop 0
	v_add_f32_e32 v19, 1.0, v19
	v_div_scale_f32 v22, s[0:1], v19, v19, v7
	v_rcp_f32_e32 v23, v22
	s_nop 0
	v_fma_f32 v26, -v22, v23, 1.0
	v_fmac_f32_e32 v23, v26, v23
	v_div_scale_f32 v26, vcc, v7, v19, v7
	v_mul_f32_e32 v27, v26, v23
	v_fma_f32 v30, -v22, v27, v26
	v_fmac_f32_e32 v27, v30, v23
	v_fma_f32 v22, -v22, v27, v26
	v_div_fmas_f32 v22, v22, v23, v27
	v_div_fixup_f32 v7, v22, v19, v7
	v_mul_f32_e32 v7, v18, v7
	v_cvt_pk_bf16_f32 v7, v7, s0
	global_store_short v[14:15], v7, off offset:32
	s_nop 0
	v_lshlrev_b32_e32 v7, 16, v182
	v_mul_f32_e32 v18, 0xbfb8aa3b, v7
	v_exp_f32_e32 v18, v18
	s_nop 0
	v_add_f32_e32 v18, 1.0, v18
	v_div_scale_f32 v19, s[0:1], v18, v18, v7
	v_rcp_f32_e32 v22, v19
	s_nop 0
	v_fma_f32 v23, -v19, v22, 1.0
	v_fmac_f32_e32 v22, v23, v22
	v_div_scale_f32 v23, vcc, v7, v18, v7
	v_mul_f32_e32 v26, v23, v22
	v_fma_f32 v27, -v19, v26, v23
	v_fmac_f32_e32 v26, v27, v22
	v_fma_f32 v19, -v19, v26, v23
	v_div_fmas_f32 v19, v19, v22, v26
	v_div_fixup_f32 v7, v19, v18, v7
	v_mul_f32_e32 v6, v6, v7
	v_cvt_pk_bf16_f32 v6, v6, s0
	global_store_short v[14:15], v6, off offset:64
	s_nop 0
	v_lshlrev_b32_e32 v6, 16, v183
	v_mul_f32_e32 v3, 0xbfb8aa3b, v6
	v_exp_f32_e32 v3, v3
	s_nop 0
	v_add_f32_e32 v3, 1.0, v3
	v_div_scale_f32 v7, s[0:1], v3, v3, v6
	v_rcp_f32_e32 v10, v7
	s_nop 0
	v_fma_f32 v11, -v7, v10, 1.0
	v_fmac_f32_e32 v10, v11, v10
	v_div_scale_f32 v11, vcc, v6, v3, v6
	v_mul_f32_e32 v18, v11, v10
	v_fma_f32 v19, -v7, v18, v11
	v_fmac_f32_e32 v18, v19, v10
	v_fma_f32 v7, -v7, v18, v11
	v_div_fmas_f32 v7, v7, v10, v18
	v_div_fixup_f32 v3, v7, v3, v6
	v_mul_f32_e32 v2, v2, v3
	v_cvt_pk_bf16_f32 v2, v2, s0
	global_store_short v[14:15], v2, off offset:96
	v_cvt_f32_i32_e32 v2, v110
	v_mov_b32_e32 v3, v4
	v_mov_b32_e32 v6, v16
	v_mov_b32_e32 v7, v12
	v_mul_f32_e32 v2, v2, v131
	v_mul_f32_e32 v2, 0xbfb8aa3b, v2
	v_exp_f32_e32 v11, v2
	v_sub_u32_e32 v2, 0x80, v111
	v_cvt_f32_i32_e32 v2, v2
	v_mov_b32_e32 v19, v32
	v_mov_b32_e32 v15, v72
	v_mul_f32_e32 v2, v2, v130
	v_mul_f32_e32 v2, 0xbfb8aa3b, v2
	v_exp_f32_e32 v10, v2
	v_mov_b32_e32 v2, v8
	v_pk_mul_f32 v[2:3], v[10:11], v[2:3]
	s_nop 0
	v_add_f32_e32 v3, v3, v68
	v_pk_mul_f32 v[6:7], v[10:11], v[6:7]
	v_add_f32_e32 v2, v2, v3
	v_add_f32_e32 v3, v7, v80
	v_add_f32_e32 v22, v6, v3
	v_mov_b32_e32 v6, v24
	v_mov_b32_e32 v7, v20
	v_pk_mul_f32 v[6:7], v[10:11], v[6:7]
	v_mul_f32_e32 v14, v22, v22
	v_add_f32_e32 v3, v7, v76
	v_add_f32_e32 v6, v6, v3
	v_mov_b32_e32 v3, v11
	v_mov_b32_e32 v18, v2
	v_pk_fma_f32 v[14:15], v[2:3], v[18:19], v[14:15]
	v_mov_b32_e32 v7, v10
	v_mov_b32_e32 v10, v6
	v_mov_b32_e32 v11, v28
	v_pk_fma_f32 v[10:11], v[6:7], v[10:11], v[14:15]
	v_add_u32_e32 v14, s6, v111
	v_mad_i64_i32 v[18:19], s[0:1], v14, s3, v[98:99]
	v_lshl_add_u64 v[18:19], v[18:19], 0, s[26:27]
	v_lshl_add_u64 v[26:27], v[18:19], 0, v[0:1]
	v_lshl_add_u64 v[18:19], v[26:27], 0, s[10:11]
	v_add_co_u32_e32 v26, vcc, s7, v26
	v_ashrrev_i32_e32 v15, 31, v14
	s_nop 0
	v_addc_co_u32_e32 v27, vcc, 0, v27, vcc
	v_lshlrev_b64 v[14:15], 11, v[14:15]
	v_lshl_add_u64 v[14:15], s[4:5], 0, v[14:15]
	v_lshl_add_u64 v[14:15], v[14:15], 0, v[0:1]
	s_nop 0
	v_lshlrev_b32_e32 v3, 16, v184
	v_mul_f32_e32 v4, 0xbfb8aa3b, v3
	v_exp_f32_e32 v4, v4
	s_nop 0
	v_add_f32_e32 v4, 1.0, v4
	v_div_scale_f32 v7, s[0:1], v4, v4, v3
	v_rcp_f32_e32 v8, v7
	s_nop 0
	v_fma_f32 v12, -v7, v8, 1.0
	v_fmac_f32_e32 v8, v12, v8
	v_div_scale_f32 v12, vcc, v3, v4, v3
	v_mul_f32_e32 v16, v12, v8
	v_fma_f32 v20, -v7, v16, v12
	v_fmac_f32_e32 v16, v20, v8
	v_fma_f32 v7, -v7, v16, v12
	v_div_fmas_f32 v7, v7, v8, v16
	v_div_fixup_f32 v3, v7, v4, v3
	s_nop 0
	v_lshlrev_b32_e32 v4, 16, v185
	v_mul_f32_e32 v7, 0xbfb8aa3b, v4
	v_exp_f32_e32 v7, v7
	s_nop 0
	v_add_f32_e32 v7, 1.0, v7
	v_div_scale_f32 v8, s[0:1], v7, v7, v4
	v_rcp_f32_e32 v12, v8
	s_nop 0
	v_fma_f32 v16, -v8, v12, 1.0
	v_fmac_f32_e32 v12, v16, v12
	v_div_scale_f32 v16, vcc, v4, v7, v4
	v_mul_f32_e32 v20, v16, v12
	v_fma_f32 v23, -v8, v20, v16
	v_fmac_f32_e32 v20, v23, v12
	v_fma_f32 v8, -v8, v20, v16
	v_div_fmas_f32 v8, v8, v12, v20
	v_div_fixup_f32 v7, v8, v7, v4
	s_nop 0
	v_lshlrev_b32_e32 v4, 16, v186
	v_mul_f32_e32 v8, 0xbfb8aa3b, v4
	v_exp_f32_e32 v8, v8
	s_nop 0
	v_add_f32_e32 v8, 1.0, v8
	v_div_scale_f32 v12, s[0:1], v8, v8, v4
	v_rcp_f32_e32 v16, v12
	s_nop 0
	v_fma_f32 v20, -v12, v16, 1.0
	v_fmac_f32_e32 v16, v20, v16
	v_div_scale_f32 v20, vcc, v4, v8, v4
	v_mul_f32_e32 v23, v20, v16
	v_fma_f32 v24, -v12, v23, v20
	v_fmac_f32_e32 v23, v24, v16
	v_fma_f32 v12, -v12, v23, v20
	v_div_fmas_f32 v12, v12, v16, v23
	v_div_fixup_f32 v23, v12, v8, v4
	s_nop 0
	v_lshlrev_b32_e32 v4, 16, v187
	v_mul_f32_e32 v8, 0xbfb8aa3b, v4
	v_exp_f32_e32 v8, v8
	s_nop 0
	v_add_f32_e32 v8, 1.0, v8
	v_div_scale_f32 v12, s[0:1], v8, v8, v4
	v_rcp_f32_e32 v16, v12
	s_nop 0
	v_fma_f32 v18, -v12, v16, 1.0
	v_fmac_f32_e32 v16, v18, v16
	v_div_scale_f32 v18, vcc, v4, v8, v4
	v_mul_f32_e32 v19, v18, v16
	v_fma_f32 v20, -v12, v19, v18
	v_fmac_f32_e32 v19, v20, v16
	v_fma_f32 v12, -v12, v19, v18
	v_div_fmas_f32 v12, v12, v16, v19
	v_div_fixup_f32 v24, v12, v8, v4
	v_add_u32_e32 v4, 20, v132
	v_cvt_f32_i32_e32 v4, v4
	v_mov_b32_e32 v12, v17
	v_mov_b32_e32 v20, v25
	v_mul_f32_e32 v4, v4, v131
	v_mul_f32_e32 v4, 0xbfb8aa3b, v4
	v_exp_f32_e32 v19, v4
	v_sub_u32_e32 v4, 0x80, v110
	v_cvt_f32_i32_e32 v4, v4
	v_mov_b32_e32 v17, v19
	v_mul_f32_e32 v4, v4, v130
	v_mul_f32_e32 v4, 0xbfb8aa3b, v4
	v_exp_f32_e32 v18, v4
	v_mov_b32_e32 v4, v9
	v_pk_mul_f32 v[4:5], v[18:19], v[4:5]
	s_nop 0
	v_add_f32_e32 v5, v5, v69
	v_add_f32_e32 v16, v4, v5
	v_pk_mul_f32 v[4:5], v[18:19], v[12:13]
	v_mov_b32_e32 v32, v16
	v_add_f32_e32 v5, v5, v81
	v_add_f32_e32 v26, v4, v5
	v_pk_mul_f32 v[4:5], v[18:19], v[20:21]
	v_mul_f32_e32 v72, v26, v26
	v_add_f32_e32 v5, v5, v77
	v_add_f32_e32 v8, v4, v5
	v_pk_fma_f32 v[4:5], v[16:17], v[32:33], v[72:73]
	v_mov_b32_e32 v9, v18
	v_mov_b32_e32 v28, v8
	v_pk_fma_f32 v[4:5], v[8:9], v[28:29], v[4:5]
	v_mov_b32_e32 v13, v11
	v_mov_b32_e32 v12, v5
	v_mov_b32_e32 v18, v4
	v_mov_b32_e32 v19, v10
	v_pk_fma_f32 v[12:13], v[12:13], v[12:13], v[18:19]
	ds_bpermute_b32 v19, v117, v13
	ds_bpermute_b32 v18, v117, v12
	s_waitcnt lgkmcnt(0)
	v_pk_add_f32 v[12:13], v[12:13], v[18:19]
	ds_bpermute_b32 v19, v116, v13
	ds_bpermute_b32 v18, v116, v12
	s_waitcnt lgkmcnt(0)
	v_pk_add_f32 v[12:13], v[12:13], v[18:19]
	ds_bpermute_b32 v19, v114, v13
	ds_bpermute_b32 v18, v114, v12
	s_waitcnt lgkmcnt(0)
	v_pk_add_f32 v[12:13], v[12:13], v[18:19]
	ds_bpermute_b32 v19, v113, v13
	ds_bpermute_b32 v18, v113, v12
	s_waitcnt lgkmcnt(0)
	v_pk_add_f32 v[12:13], v[12:13], v[18:19]
	s_nop 0
	v_pk_fma_f32 v[12:13], v[12:13], s[12:13], v[34:35] op_sel_hi:[1,0,0]
	s_nop 0
	v_mul_f32_e32 v4, 0x4b800000, v13
	v_cmp_gt_f32_e64 s[0:1], s8, v13
	v_cmp_gt_f32_e32 vcc, s8, v12
	s_nop 0
	v_cndmask_b32_e64 v4, v13, v4, s[0:1]
	v_rsq_f32_e32 v4, v4
	s_nop 0
	v_mul_f32_e32 v9, 0x45800000, v4
	v_cndmask_b32_e64 v4, v4, v9, s[0:1]
	v_mul_f32_e32 v2, v2, v4
	v_mul_f32_e32 v2, v3, v2
	v_cvt_pk_bf16_f32 v2, v2, s0
	global_store_short v[14:15], v2, off
	v_mul_f32_e32 v2, v22, v4
	v_mul_f32_e32 v2, v2, v7
	v_cvt_pk_bf16_f32 v2, v2, s0
	global_store_short v[14:15], v2, off offset:32
	v_mul_f32_e32 v2, v6, v4
	v_mul_f32_e32 v2, v2, v23
	v_cvt_pk_bf16_f32 v2, v2, s0
	global_store_short v[14:15], v2, off offset:64
	v_mul_f32_e32 v2, v11, v4
	v_mul_f32_e32 v2, v2, v24
	v_cvt_pk_bf16_f32 v2, v2, s0
	global_store_short v[14:15], v2, off offset:96
	v_mul_f32_e32 v2, 0x4b800000, v12
	v_cndmask_b32_e32 v2, v12, v2, vcc
	v_rsq_f32_e32 v2, v2
	s_nop 0
	v_mul_f32_e32 v3, 0x45800000, v2
	v_cndmask_b32_e32 v4, v2, v3, vcc
	v_add_u32_e32 v2, s6, v110
	v_mad_i64_i32 v[6:7], s[0:1], v2, s3, v[98:99]
	v_lshl_add_u64 v[6:7], v[6:7], 0, s[26:27]
	v_lshl_add_u64 v[10:11], v[6:7], 0, v[0:1]
	v_lshl_add_u64 v[6:7], v[10:11], 0, s[10:11]
	v_add_co_u32_e32 v10, vcc, s7, v10
	v_ashrrev_i32_e32 v3, 31, v2
	s_nop 0
	v_addc_co_u32_e32 v11, vcc, 0, v11, vcc
	v_lshlrev_b64 v[2:3], 11, v[2:3]
	v_lshl_add_u64 v[2:3], s[4:5], 0, v[2:3]
	v_lshl_add_u64 v[2:3], v[2:3], 0, v[0:1]
	v_mul_f32_e32 v10, v16, v4
	v_mul_f32_e32 v8, v8, v4
	s_nop 0
	v_lshlrev_b32_e32 v9, 16, v188
	v_mul_f32_e32 v11, 0xbfb8aa3b, v9
	v_exp_f32_e32 v11, v11
	s_nop 0
	v_lshlrev_b32_e32 v0, 16, v189
	v_add_f32_e32 v11, 1.0, v11
	v_div_scale_f32 v12, s[0:1], v11, v11, v9
	v_rcp_f32_e32 v13, v12
	s_nop 0
	v_fma_f32 v14, -v12, v13, 1.0
	v_fmac_f32_e32 v13, v14, v13
	v_div_scale_f32 v14, vcc, v9, v11, v9
	v_mul_f32_e32 v15, v14, v13
	v_fma_f32 v16, -v12, v15, v14
	v_fmac_f32_e32 v15, v16, v13
	v_fma_f32 v12, -v12, v15, v14
	v_div_fmas_f32 v12, v12, v13, v15
	v_div_fixup_f32 v9, v12, v11, v9
	v_mul_f32_e32 v9, v9, v10
	v_mul_f32_e32 v10, 0xbfb8aa3b, v0
	v_exp_f32_e32 v10, v10
	v_cvt_pk_bf16_f32 v9, v9, s0
	global_store_short v[2:3], v9, off
	v_mul_f32_e32 v9, v26, v4
	v_add_f32_e32 v10, 1.0, v10
	v_div_scale_f32 v11, s[0:1], v10, v10, v0
	v_rcp_f32_e32 v12, v11
	v_mul_f32_e32 v4, v5, v4
	v_fma_f32 v13, -v11, v12, 1.0
	v_fmac_f32_e32 v12, v13, v12
	v_div_scale_f32 v13, vcc, v0, v10, v0
	v_mul_f32_e32 v14, v13, v12
	v_fma_f32 v15, -v11, v14, v13
	v_fmac_f32_e32 v14, v15, v12
	v_fma_f32 v11, -v11, v14, v13
	v_div_fmas_f32 v11, v11, v12, v14
	v_div_fixup_f32 v0, v11, v10, v0
	v_mul_f32_e32 v0, v9, v0
	v_cvt_pk_bf16_f32 v0, v0, s0
	global_store_short v[2:3], v0, off offset:32
	s_nop 0
	v_lshlrev_b32_e32 v0, 16, v190
	v_mul_f32_e32 v9, 0xbfb8aa3b, v0
	v_exp_f32_e32 v9, v9
	s_nop 0
	v_add_f32_e32 v9, 1.0, v9
	v_div_scale_f32 v10, s[0:1], v9, v9, v0
	v_rcp_f32_e32 v11, v10
	s_nop 0
	v_fma_f32 v12, -v10, v11, 1.0
	v_fmac_f32_e32 v11, v12, v11
	v_div_scale_f32 v12, vcc, v0, v9, v0
	v_mul_f32_e32 v13, v12, v11
	v_fma_f32 v14, -v10, v13, v12
	v_fmac_f32_e32 v13, v14, v11
	v_fma_f32 v10, -v10, v13, v12
	v_div_fmas_f32 v10, v10, v11, v13
	v_div_fixup_f32 v0, v10, v9, v0
	v_mul_f32_e32 v0, v8, v0
	v_cvt_pk_bf16_f32 v0, v0, s0
	global_store_short v[2:3], v0, off offset:64
	s_nop 0
	v_lshlrev_b32_e32 v0, 16, v191
	v_mul_f32_e32 v5, 0xbfb8aa3b, v0
	v_exp_f32_e32 v5, v5
	s_nop 0
	v_add_f32_e32 v5, 1.0, v5
	v_div_scale_f32 v6, s[0:1], v5, v5, v0
	v_rcp_f32_e32 v7, v6
	s_nop 0
	v_fma_f32 v8, -v6, v7, 1.0
	v_fmac_f32_e32 v7, v8, v7
	v_div_scale_f32 v8, vcc, v0, v5, v0
	v_mul_f32_e32 v9, v8, v7
	v_fma_f32 v10, -v6, v9, v8
	v_fmac_f32_e32 v9, v10, v7
	v_fma_f32 v6, -v6, v9, v8
	v_div_fmas_f32 v6, v6, v7, v9
	v_div_fixup_f32 v0, v6, v5, v0
	v_mul_f32_e32 v0, v4, v0
	v_cvt_pk_bf16_f32 v0, v0, s0
	global_store_short v[2:3], v0, off offset:96
	s_barrier
	s_branch .LBB0_184

.LBB0_327:
	s_or_b64 exec, exec, s[6:7]
	s_xor_b64 s[6:7], s[8:9], -1
	s_waitcnt vmcnt(0)
	v_lshlrev_b32_e32 v103, 16, v103
	v_lshlrev_b32_e32 v99, 16, v99
	v_lshlrev_b32_e32 v101, 16, v101
	v_lshlrev_b32_e32 v95, 16, v95
	v_lshlrev_b32_e32 v97, 16, v97
	v_lshlrev_b32_e32 v91, 16, v91
	v_lshlrev_b32_e32 v93, 16, v93
	v_lshlrev_b32_e32 v89, 16, v89
	v_lshlrev_b32_e32 v88, 16, v14
	v_and_b32_e32 v104, 0xffff0000, v14
	v_lshlrev_b32_e32 v105, 16, v15
	v_pk_mov_b32 v[14:15], v[14:15], v[16:17] op_sel:[1,0]
	v_and_b32_e32 v109, 16, v17
	v_and_b32_e32 v15, 16, v15
	v_and_b32_e32 v14, 0xffff0000, v14
	v_and_b32_e32 v108, 0xffff0000, v16
	v_lshlrev_b32_e32 v111, 16, v17
	v_and_b32_e32 v113, 0xffff0000, v17
	v_lshlrev_b32_e32 v17, 16, v16
	v_mov_b32_e32 v16, v14
	v_pk_mov_b32 v[14:15], v[104:105], v[14:15] op_sel:[1,0]
	v_mov_b32_e32 v102, v104
	v_pk_mul_f32 v[14:15], v[80:81], v[14:15]
	v_pk_mul_f32 v[102:103], v[86:87], v[102:103]
	v_pk_fma_f32 v[14:15], v[78:79], v[104:105], v[14:15]
	v_pk_fma_f32 v[102:103], v[86:87], v[88:89], v[102:103] op_sel:[0,0,1] op_sel_hi:[1,0,0]
	v_pk_fma_f32 v[14:15], v[84:85], v[16:17], v[14:15]
	v_pk_fma_f32 v[102:103], v[84:85], v[104:105], v[102:103]
	v_pk_add_f32 v[104:105], v[82:83], v[14:15]
	v_pk_mov_b32 v[14:15], v[16:17], v[108:109] op_sel:[1,0]
	v_mov_b32_e32 v110, v108
	v_pk_mul_f32 v[14:15], v[80:81], v[14:15]
	v_mov_b32_e32 v112, v111
	v_pk_fma_f32 v[14:15], v[78:79], v[16:17], v[14:15]
	v_mov_b32_e32 v98, v113
	v_pk_fma_f32 v[14:15], v[84:85], v[110:111], v[14:15]
	v_pk_add_f32 v[102:103], v[82:83], v[102:103]
	v_pk_add_f32 v[16:17], v[82:83], v[14:15]
	v_pk_mul_f32 v[14:15], v[80:81], v[112:113]
	v_lshlrev_b32_e32 v33, 7, v33
	v_pk_fma_f32 v[14:15], v[78:79], v[110:111], v[14:15]
	v_lshlrev_b32_e32 v31, 4, v31
	v_pk_fma_f32 v[14:15], v[84:85], v[98:99], v[14:15]
	v_cvt_pk_bf16_f32 v16, v16, v17
	v_pk_add_f32 v[98:99], v[82:83], v[14:15]
	v_cvt_pk_bf16_f32 v14, v102, v103
	v_cvt_pk_bf16_f32 v15, v104, v105
	v_cvt_pk_bf16_f32 v17, v98, v99
	v_add3_u32 v31, 0, v33, v31
	ds_write_b128 v31, v[14:17]
	s_waitcnt vmcnt(2)
	v_lshlrev_b32_e32 v14, 16, v10
	v_and_b32_e32 v16, 0xffff0000, v10
	v_lshlrev_b32_e32 v17, 16, v11
	v_pk_mov_b32 v[10:11], v[10:11], v[12:13] op_sel:[1,0]
	v_and_b32_e32 v99, 16, v13
	v_and_b32_e32 v11, 16, v11
	v_and_b32_e32 v10, 0xffff0000, v10
	v_and_b32_e32 v98, 0xffff0000, v12
	v_lshlrev_b32_e32 v103, 16, v13
	v_and_b32_e32 v105, 0xffff0000, v13
	v_lshlrev_b32_e32 v13, 16, v12
	v_mov_b32_e32 v12, v10
	v_pk_mov_b32 v[10:11], v[16:17], v[10:11] op_sel:[1,0]
	v_mov_b32_e32 v100, v16
	v_pk_mul_f32 v[10:11], v[80:81], v[10:11]
	v_pk_mul_f32 v[100:101], v[86:87], v[100:101]
	v_pk_fma_f32 v[10:11], v[78:79], v[16:17], v[10:11]
	v_pk_fma_f32 v[14:15], v[86:87], v[14:15], v[100:101] op_sel:[0,0,1] op_sel_hi:[1,0,0]
	v_pk_fma_f32 v[10:11], v[84:85], v[12:13], v[10:11]
	v_pk_fma_f32 v[14:15], v[84:85], v[16:17], v[14:15]
	v_pk_add_f32 v[16:17], v[82:83], v[10:11]
	v_pk_mov_b32 v[10:11], v[12:13], v[98:99] op_sel:[1,0]
	v_mov_b32_e32 v102, v98
	v_pk_mul_f32 v[10:11], v[80:81], v[10:11]
	v_mov_b32_e32 v104, v103
	v_pk_fma_f32 v[10:11], v[78:79], v[12:13], v[10:11]
	v_mov_b32_e32 v94, v105
	v_pk_fma_f32 v[10:11], v[84:85], v[102:103], v[10:11]
	v_pk_add_f32 v[14:15], v[82:83], v[14:15]
	v_pk_add_f32 v[12:13], v[82:83], v[10:11]
	v_pk_mul_f32 v[10:11], v[80:81], v[104:105]
	v_cvt_pk_bf16_f32 v12, v12, v13
	v_pk_fma_f32 v[10:11], v[78:79], v[102:103], v[10:11]
	s_movk_i32 s1, 0x400
	v_pk_fma_f32 v[10:11], v[84:85], v[94:95], v[10:11]
	s_mov_b64 s[8:9], 0
	v_pk_add_f32 v[94:95], v[82:83], v[10:11]
	v_cvt_pk_bf16_f32 v10, v14, v15
	v_lshlrev_b32_e32 v14, 7, v29
	v_lshlrev_b32_e32 v15, 4, v27
	v_cvt_pk_bf16_f32 v11, v16, v17
	v_cvt_pk_bf16_f32 v13, v94, v95
	v_add3_u32 v14, 0, v14, v15
	ds_write_b128 v14, v[10:13]
	s_waitcnt vmcnt(1)
	v_lshlrev_b32_e32 v10, 16, v6
	v_and_b32_e32 v12, 0xffff0000, v6
	v_lshlrev_b32_e32 v13, 16, v7
	v_pk_mov_b32 v[6:7], v[6:7], v[8:9] op_sel:[1,0]
	v_and_b32_e32 v15, 16, v9
	v_and_b32_e32 v7, 16, v7
	v_and_b32_e32 v6, 0xffff0000, v6
	v_and_b32_e32 v14, 0xffff0000, v8
	v_lshlrev_b32_e32 v17, 16, v9
	v_and_b32_e32 v95, 0xffff0000, v9
	v_lshlrev_b32_e32 v9, 16, v8
	v_mov_b32_e32 v8, v6
	v_pk_mov_b32 v[6:7], v[12:13], v[6:7] op_sel:[1,0]
	v_mov_b32_e32 v96, v12
	v_pk_mul_f32 v[6:7], v[80:81], v[6:7]
	v_pk_mul_f32 v[96:97], v[86:87], v[96:97]
	v_pk_fma_f32 v[6:7], v[78:79], v[12:13], v[6:7]
	v_pk_fma_f32 v[10:11], v[86:87], v[10:11], v[96:97] op_sel:[0,0,1] op_sel_hi:[1,0,0]
	v_pk_fma_f32 v[6:7], v[84:85], v[8:9], v[6:7]
	v_pk_fma_f32 v[10:11], v[84:85], v[12:13], v[10:11]
	v_pk_add_f32 v[12:13], v[82:83], v[6:7]
	v_pk_mov_b32 v[6:7], v[8:9], v[14:15] op_sel:[1,0]
	v_mov_b32_e32 v16, v14
	v_pk_mul_f32 v[6:7], v[80:81], v[6:7]
	v_mov_b32_e32 v94, v17
	v_pk_fma_f32 v[6:7], v[78:79], v[8:9], v[6:7]
	v_mov_b32_e32 v90, v95
	v_pk_fma_f32 v[6:7], v[84:85], v[16:17], v[6:7]
	v_pk_add_f32 v[10:11], v[82:83], v[10:11]
	v_pk_add_f32 v[8:9], v[82:83], v[6:7]
	v_pk_mul_f32 v[6:7], v[80:81], v[94:95]
	v_cvt_pk_bf16_f32 v8, v8, v9
	v_pk_fma_f32 v[6:7], v[78:79], v[16:17], v[6:7]
	s_and_b64 vcc, exec, s[6:7]
	v_pk_fma_f32 v[6:7], v[84:85], v[90:91], v[6:7]
	s_nop 0
	v_pk_add_f32 v[14:15], v[82:83], v[6:7]
	v_cvt_pk_bf16_f32 v6, v10, v11
	v_lshlrev_b32_e32 v10, 7, v25
	v_lshlrev_b32_e32 v11, 4, v23
	v_cvt_pk_bf16_f32 v7, v12, v13
	v_cvt_pk_bf16_f32 v9, v14, v15
	v_add3_u32 v10, 0, v10, v11
	ds_write_b128 v10, v[6:9]
	s_waitcnt vmcnt(0)
	v_lshlrev_b32_e32 v6, 16, v2
	v_and_b32_e32 v8, 0xffff0000, v2
	v_lshlrev_b32_e32 v9, 16, v3
	v_pk_mov_b32 v[2:3], v[2:3], v[4:5] op_sel:[1,0]
	v_and_b32_e32 v11, 16, v5
	v_and_b32_e32 v3, 16, v3
	v_and_b32_e32 v2, 0xffff0000, v2
	v_and_b32_e32 v10, 0xffff0000, v4
	v_lshlrev_b32_e32 v13, 16, v5
	v_and_b32_e32 v15, 0xffff0000, v5
	v_lshlrev_b32_e32 v5, 16, v4
	v_mov_b32_e32 v4, v2
	v_pk_mov_b32 v[2:3], v[8:9], v[2:3] op_sel:[1,0]
	v_mov_b32_e32 v92, v8
	v_pk_mul_f32 v[2:3], v[80:81], v[2:3]
	v_pk_mul_f32 v[16:17], v[86:87], v[92:93]
	v_pk_fma_f32 v[2:3], v[78:79], v[8:9], v[2:3]
	v_pk_fma_f32 v[6:7], v[86:87], v[6:7], v[16:17] op_sel:[0,0,1] op_sel_hi:[1,0,0]
	v_pk_fma_f32 v[2:3], v[84:85], v[4:5], v[2:3]
	v_pk_fma_f32 v[6:7], v[84:85], v[8:9], v[6:7]
	v_pk_add_f32 v[8:9], v[82:83], v[2:3]
	v_pk_mov_b32 v[2:3], v[4:5], v[10:11] op_sel:[1,0]
	v_mov_b32_e32 v12, v10
	v_pk_mul_f32 v[2:3], v[80:81], v[2:3]
	v_mov_b32_e32 v14, v13
	v_pk_fma_f32 v[2:3], v[78:79], v[4:5], v[2:3]
	v_mov_b32_e32 v88, v15
	v_pk_fma_f32 v[2:3], v[84:85], v[12:13], v[2:3]
	v_pk_add_f32 v[6:7], v[82:83], v[6:7]
	v_pk_add_f32 v[4:5], v[82:83], v[2:3]
	v_pk_mul_f32 v[2:3], v[80:81], v[14:15]
	v_cvt_pk_bf16_f32 v4, v4, v5
	v_pk_fma_f32 v[2:3], v[78:79], v[12:13], v[2:3]
	s_nop 0
	v_pk_fma_f32 v[2:3], v[84:85], v[88:89], v[2:3]
	s_nop 0
	v_pk_add_f32 v[10:11], v[82:83], v[2:3]
	v_cvt_pk_bf16_f32 v2, v6, v7
	v_lshlrev_b32_e32 v6, 7, v21
	v_lshlrev_b32_e32 v7, 4, v19
	v_cvt_pk_bf16_f32 v3, v8, v9
	v_cvt_pk_bf16_f32 v5, v10, v11
	v_add3_u32 v6, 0, v6, v7
	ds_write_b128 v6, v[2:5]
	s_cbranch_vccnz .LBB0_346
.LBB0_328:
	v_add_u32_e32 v4, s1, v106
	v_ashrrev_i32_e32 v2, 31, v4
	v_add_u32_sdwa v2, v4, v2 dst_sel:DWORD dst_unused:UNUSED_PAD src0_sel:DWORD src1_sel:BYTE_3
	v_ashrrev_i32_e32 v31, 8, v2
	v_mul_i32_i24_e32 v2, 0x100, v31
	v_sub_u32_e32 v33, v4, v2
	v_lshlrev_b32_e32 v2, 11, v31
	v_ashrrev_i32_e32 v3, 31, v2
	v_lshlrev_b32_e32 v6, 3, v33
	v_lshl_add_u64 v[2:3], v[2:3], 1, s[4:5]
	v_ashrrev_i32_e32 v7, 31, v6
	v_lshl_add_u64 v[2:3], v[6:7], 1, v[2:3]
	global_load_dwordx4 v[14:17], v[2:3], off
	v_cmp_lt_i32_e32 vcc, 0, v33
	v_mov_b32_e32 v99, 0
	v_mov_b32_e32 v103, 0
	s_and_saveexec_b64 s[6:7], vcc
	s_cbranch_execz .LBB0_330
	global_load_ushort v103, v[2:3], off offset:-2
.LBB0_330:
	s_or_b64 exec, exec, s[6:7]
	v_cmp_gt_i32_e32 vcc, s33, v33
	s_and_saveexec_b64 s[6:7], vcc
	s_cbranch_execz .LBB0_332
	global_load_ushort v99, v[2:3], off offset:16
.LBB0_332:
	s_or_b64 exec, exec, s[6:7]
	v_add_u32_e32 v2, 0x100, v4
	v_ashrrev_i32_e32 v3, 31, v2
	v_add_u32_sdwa v3, v2, v3 dst_sel:DWORD dst_unused:UNUSED_PAD src0_sel:DWORD src1_sel:BYTE_3
	v_ashrrev_i32_e32 v27, 8, v3
	v_mul_i32_i24_e32 v3, 0x100, v27
	v_sub_u32_e32 v29, v2, v3
	v_lshlrev_b32_e32 v2, 11, v27
	v_ashrrev_i32_e32 v3, 31, v2
	v_lshlrev_b32_e32 v6, 3, v29
	v_lshl_add_u64 v[2:3], v[2:3], 1, s[4:5]
	v_ashrrev_i32_e32 v7, 31, v6
	v_lshl_add_u64 v[2:3], v[6:7], 1, v[2:3]
	global_load_dwordx4 v[10:13], v[2:3], off
	v_cmp_lt_i32_e32 vcc, 0, v29
	v_mov_b32_e32 v95, 0
	v_mov_b32_e32 v101, 0
	s_and_saveexec_b64 s[6:7], vcc
	s_cbranch_execz .LBB0_334
	global_load_ushort v101, v[2:3], off offset:-2
.LBB0_334:
	s_or_b64 exec, exec, s[6:7]
	v_cmp_gt_i32_e32 vcc, s33, v29
	s_and_saveexec_b64 s[6:7], vcc
	s_cbranch_execz .LBB0_336
	global_load_ushort v95, v[2:3], off offset:16
.LBB0_336:
	s_or_b64 exec, exec, s[6:7]
	v_add_u32_e32 v2, 0x200, v4
	v_ashrrev_i32_e32 v3, 31, v2
	v_add_u32_sdwa v3, v2, v3 dst_sel:DWORD dst_unused:UNUSED_PAD src0_sel:DWORD src1_sel:BYTE_3
	v_ashrrev_i32_e32 v23, 8, v3
	v_mul_i32_i24_e32 v3, 0x100, v23
	v_sub_u32_e32 v25, v2, v3
	v_lshlrev_b32_e32 v2, 11, v23
	v_ashrrev_i32_e32 v3, 31, v2
	v_lshlrev_b32_e32 v6, 3, v25
	v_lshl_add_u64 v[2:3], v[2:3], 1, s[4:5]
	v_ashrrev_i32_e32 v7, 31, v6
	v_lshl_add_u64 v[2:3], v[6:7], 1, v[2:3]
	global_load_dwordx4 v[6:9], v[2:3], off
	v_cmp_lt_i32_e32 vcc, 0, v25
	v_mov_b32_e32 v91, 0
	v_mov_b32_e32 v97, 0
	s_and_saveexec_b64 s[6:7], vcc
	s_cbranch_execz .LBB0_338
	global_load_ushort v97, v[2:3], off offset:-2
.LBB0_338:
	s_or_b64 exec, exec, s[6:7]
	v_cmp_gt_i32_e32 vcc, s33, v25
	s_and_saveexec_b64 s[6:7], vcc
	s_cbranch_execz .LBB0_340
	global_load_ushort v91, v[2:3], off offset:16
.LBB0_340:
	s_or_b64 exec, exec, s[6:7]
	v_add_u32_e32 v2, 0x300, v4
	v_ashrrev_i32_e32 v3, 31, v2
	v_add_u32_sdwa v3, v2, v3 dst_sel:DWORD dst_unused:UNUSED_PAD src0_sel:DWORD src1_sel:BYTE_3
	v_ashrrev_i32_e32 v19, 8, v3
	v_mul_i32_i24_e32 v3, 0x100, v19
	v_sub_u32_e32 v21, v2, v3
	v_lshlrev_b32_e32 v2, 11, v19
	v_ashrrev_i32_e32 v3, 31, v2
	v_lshlrev_b32_e32 v4, 3, v21
	v_lshl_add_u64 v[2:3], v[2:3], 1, s[4:5]
	v_ashrrev_i32_e32 v5, 31, v4
	v_lshl_add_u64 v[104:105], v[4:5], 1, v[2:3]
	global_load_dwordx4 v[2:5], v[104:105], off
	v_cmp_lt_i32_e32 vcc, 0, v21
	v_mov_b32_e32 v89, 0
	v_mov_b32_e32 v93, 0
	s_and_saveexec_b64 s[6:7], vcc
	s_cbranch_execz .LBB0_342
	global_load_ushort v93, v[104:105], off offset:-2
.LBB0_342:
	s_or_b64 exec, exec, s[6:7]
	v_cmp_gt_i32_e32 vcc, s33, v21
	s_and_saveexec_b64 s[6:7], vcc
	s_cbranch_execz .LBB0_327
	global_load_ushort v89, v[104:105], off offset:16
	s_branch .LBB0_327
